# GEMM K-loops: per-segment s_setprio 1/0 flips around the MFMA blocks removed (all four loop copies)
# speedup vs baseline: 1.0126x; 1.0126x over previous
.LBB0_173:
	s_add_u32 s64, s62, 0x100
	s_addc_u32 s65, s63, 0
	s_add_i32 s34, 0, 0x10000
	v_add_u32_e32 v108, s34, v196
	ds_read_b128 v[96:99], v108
	ds_read_b128 v[100:103], v108 offset:1024
	ds_read_b128 v[104:107], v108 offset:2048
	ds_read_b128 v[158:161], v108 offset:3072
	s_cmp_eq_u32 s83, 28
	s_cselect_b32 s69, s57, s65
	s_cselect_b32 s68, s71, s64
	s_cselect_b32 s67, s55, s82
	s_cselect_b32 s66, s80, s81
	v_lshl_add_u64 v[108:109], s[62:63], 0, v[154:155]
	s_add_i32 m0, s44, 0xc000
	ds_read_b128 v[162:165], v207
	ds_read_b128 v[166:169], v207 offset:1024
	ds_read_b128 v[170:173], v207 offset:2048
	ds_read_b128 v[180:183], v207 offset:3072
	ds_read_b128 v[184:187], v207 offset:4096
	ds_read_b128 v[188:191], v207 offset:5120
	ds_read_b128 v[192:195], v207 offset:6144
	ds_read_b128 v[198:201], v207 offset:7168
	global_load_lds_dwordx4 v[108:109], off
	v_lshl_add_u64 v[108:109], s[62:63], 0, v[156:157]
	s_add_i32 m0, s44, 0xe000
	s_nop 0
	global_load_lds_dwordx4 v[108:109], off
	s_waitcnt lgkmcnt(8)
	s_barrier
	s_waitcnt lgkmcnt(0)
	s_waitcnt lgkmcnt(0)
	v_mfma_f32_16x16x32_bf16 v[138:141], v[96:99], v[162:165], v[138:141]
	v_mfma_f32_16x16x32_bf16 v[60:63], v[104:107], v[162:165], v[60:63]
	v_mfma_f32_16x16x32_bf16 v[134:137], v[96:99], v[170:173], v[134:137]
	v_mfma_f32_16x16x32_bf16 v[56:59], v[104:107], v[170:173], v[56:59]
	v_mfma_f32_16x16x32_bf16 v[130:133], v[96:99], v[184:187], v[130:133]
	v_mfma_f32_16x16x32_bf16 v[52:55], v[104:107], v[184:187], v[52:55]
	v_mfma_f32_16x16x32_bf16 v[126:129], v[96:99], v[192:195], v[126:129]
	v_mfma_f32_16x16x32_bf16 v[48:51], v[104:107], v[192:195], v[48:51]
	v_mfma_f32_16x16x32_bf16 v[138:141], v[100:103], v[166:169], v[138:141]
	v_mfma_f32_16x16x32_bf16 v[60:63], v[158:161], v[166:169], v[60:63]
	v_mfma_f32_16x16x32_bf16 v[134:137], v[100:103], v[180:183], v[134:137]
	v_mfma_f32_16x16x32_bf16 v[56:59], v[158:161], v[180:183], v[56:59]
	v_mfma_f32_16x16x32_bf16 v[130:133], v[100:103], v[188:191], v[130:133]
	v_mfma_f32_16x16x32_bf16 v[52:55], v[158:161], v[188:191], v[52:55]
	v_mfma_f32_16x16x32_bf16 v[126:129], v[100:103], v[198:201], v[126:129]
	v_mfma_f32_16x16x32_bf16 v[48:51], v[158:161], v[198:201], v[48:51]
	s_barrier
	s_add_i32 s35, 0, 0x14000
	s_add_i32 s34, s34, s39
	v_add_u32_e32 v108, s35, v196
	v_lshl_add_u64 v[174:175], s[66:67], 0, v[146:147]
	s_mov_b32 m0, s34
	ds_read_b128 v[208:211], v108
	ds_read_b128 v[212:215], v108 offset:1024
	ds_read_b128 v[216:219], v108 offset:2048
	ds_read_b128 v[220:223], v108 offset:3072
	global_load_lds_dwordx4 v[174:175], off
	v_lshl_add_u64 v[224:225], s[66:67], 0, v[142:143]
	s_add_i32 m0, s34, 0x2000
	s_nop 0
	global_load_lds_dwordx4 v[224:225], off
	s_barrier
	s_waitcnt lgkmcnt(0)
	s_waitcnt lgkmcnt(0)
	v_mfma_f32_16x16x32_bf16 v[122:125], v[208:211], v[162:165], v[122:125]
	v_mfma_f32_16x16x32_bf16 v[44:47], v[216:219], v[162:165], v[44:47]
	v_mfma_f32_16x16x32_bf16 v[114:117], v[208:211], v[170:173], v[114:117]
	v_mfma_f32_16x16x32_bf16 v[36:39], v[216:219], v[170:173], v[36:39]
	v_mfma_f32_16x16x32_bf16 v[118:121], v[208:211], v[184:187], v[118:121]
	v_mfma_f32_16x16x32_bf16 v[40:43], v[216:219], v[184:187], v[40:43]
	v_mfma_f32_16x16x32_bf16 v[108:111], v[208:211], v[192:195], v[110:113]
	v_mfma_f32_16x16x32_bf16 v[32:35], v[216:219], v[192:195], v[32:35]
	v_mfma_f32_16x16x32_bf16 v[122:125], v[212:215], v[166:169], v[122:125]
	v_mfma_f32_16x16x32_bf16 v[44:47], v[220:223], v[166:169], v[44:47]
	v_mfma_f32_16x16x32_bf16 v[114:117], v[212:215], v[180:183], v[114:117]
	v_mfma_f32_16x16x32_bf16 v[36:39], v[220:223], v[180:183], v[36:39]
	v_mfma_f32_16x16x32_bf16 v[118:121], v[212:215], v[188:191], v[118:121]
	v_mfma_f32_16x16x32_bf16 v[40:43], v[220:223], v[188:191], v[40:43]
	v_mfma_f32_16x16x32_bf16 v[108:111], v[212:215], v[198:201], v[108:111]
	v_mfma_f32_16x16x32_bf16 v[32:35], v[220:223], v[198:201], v[32:35]
	s_mov_b32 m0, s44
	v_lshl_add_u64 v[226:227], s[68:69], 0, v[148:149]
	s_barrier
	ds_read_b128 v[162:165], v207 offset:16384
	ds_read_b128 v[166:169], v207 offset:17408
	ds_read_b128 v[170:173], v207 offset:18432
	ds_read_b128 v[180:183], v207 offset:19456
	ds_read_b128 v[184:187], v207 offset:20480
	ds_read_b128 v[188:191], v207 offset:21504
	ds_read_b128 v[192:195], v207 offset:22528
	ds_read_b128 v[198:201], v207 offset:23552
	global_load_lds_dwordx4 v[226:227], off
	v_lshl_add_u64 v[228:229], s[68:69], 0, v[144:145]
	s_mov_b32 m0, s72
	s_nop 0
	global_load_lds_dwordx4 v[228:229], off
	s_barrier
	s_waitcnt lgkmcnt(0)
	s_waitcnt lgkmcnt(0)
	v_mfma_f32_16x16x32_bf16 v[92:95], v[96:99], v[162:165], v[92:95]
	v_mfma_f32_16x16x32_bf16 v[28:31], v[104:107], v[162:165], v[28:31]
	v_mfma_f32_16x16x32_bf16 v[88:91], v[96:99], v[170:173], v[88:91]
	v_mfma_f32_16x16x32_bf16 v[24:27], v[104:107], v[170:173], v[24:27]
	v_mfma_f32_16x16x32_bf16 v[84:87], v[96:99], v[184:187], v[84:87]
	v_mfma_f32_16x16x32_bf16 v[20:23], v[104:107], v[184:187], v[20:23]
	v_mfma_f32_16x16x32_bf16 v[80:83], v[96:99], v[192:195], v[80:83]
	v_mfma_f32_16x16x32_bf16 v[16:19], v[104:107], v[192:195], v[16:19]
	v_mfma_f32_16x16x32_bf16 v[92:95], v[100:103], v[166:169], v[92:95]
	v_mfma_f32_16x16x32_bf16 v[28:31], v[158:161], v[166:169], v[28:31]
	v_mfma_f32_16x16x32_bf16 v[88:91], v[100:103], v[180:183], v[88:91]
	v_mfma_f32_16x16x32_bf16 v[24:27], v[158:161], v[180:183], v[24:27]
	v_mfma_f32_16x16x32_bf16 v[84:87], v[100:103], v[188:191], v[84:87]
	v_mfma_f32_16x16x32_bf16 v[20:23], v[158:161], v[188:191], v[20:23]
	v_mfma_f32_16x16x32_bf16 v[80:83], v[100:103], v[198:201], v[80:83]
	v_mfma_f32_16x16x32_bf16 v[16:19], v[158:161], v[198:201], v[16:19]
	s_barrier
	s_add_u32 s62, s66, 0x80000
	s_addc_u32 s63, s67, 0
	s_add_i32 s34, s35, s39
	v_lshl_add_u64 v[96:97], s[62:63], 0, v[146:147]
	s_mov_b32 m0, s34
	s_nop 0
	global_load_lds_dwordx4 v[96:97], off
	v_lshl_add_u64 v[96:97], s[62:63], 0, v[142:143]
	s_add_i32 m0, s34, 0x2000
	s_nop 0
	global_load_lds_dwordx4 v[96:97], off
	s_waitcnt vmcnt(6)
	s_barrier
	v_mfma_f32_16x16x32_bf16 v[76:79], v[208:211], v[162:165], v[76:79]
	v_mfma_f32_16x16x32_bf16 v[12:15], v[216:219], v[162:165], v[12:15]
	v_mfma_f32_16x16x32_bf16 v[68:71], v[208:211], v[170:173], v[68:71]
	v_mfma_f32_16x16x32_bf16 v[4:7], v[216:219], v[170:173], v[4:7]
	v_mfma_f32_16x16x32_bf16 v[72:75], v[208:211], v[184:187], v[72:75]
	v_mfma_f32_16x16x32_bf16 v[8:11], v[216:219], v[184:187], v[8:11]
	v_mfma_f32_16x16x32_bf16 v[64:67], v[208:211], v[192:195], v[64:67]
	v_mfma_f32_16x16x32_bf16 v[0:3], v[216:219], v[192:195], v[0:3]
	v_mfma_f32_16x16x32_bf16 v[76:79], v[212:215], v[166:169], v[76:79]
	v_mfma_f32_16x16x32_bf16 v[12:15], v[220:223], v[166:169], v[12:15]
	v_mfma_f32_16x16x32_bf16 v[68:71], v[212:215], v[180:183], v[68:71]
	v_mfma_f32_16x16x32_bf16 v[4:7], v[220:223], v[180:183], v[4:7]
	v_mfma_f32_16x16x32_bf16 v[72:75], v[212:215], v[188:191], v[72:75]
	v_mfma_f32_16x16x32_bf16 v[8:11], v[220:223], v[188:191], v[8:11]
	v_mfma_f32_16x16x32_bf16 v[64:67], v[212:215], v[198:201], v[64:67]
	v_mfma_f32_16x16x32_bf16 v[0:3], v[220:223], v[198:201], v[0:3]
	s_add_i32 s34, 0, 0x18000
	v_add_u32_e32 v112, s34, v196
	s_barrier
	ds_read_b128 v[96:99], v112
	ds_read_b128 v[100:103], v112 offset:1024
	ds_read_b128 v[104:107], v112 offset:2048
	ds_read_b128 v[158:161], v112 offset:3072
	s_add_u32 s62, s68, 0x80000
	s_addc_u32 s63, s69, 0
	s_mov_b32 m0, s73
	v_lshl_add_u64 v[112:113], s[62:63], 0, v[148:149]
	ds_read_b128 v[162:165], v207 offset:32768
	ds_read_b128 v[166:169], v207 offset:33792
	ds_read_b128 v[170:173], v207 offset:34816
	ds_read_b128 v[180:183], v207 offset:35840
	ds_read_b128 v[184:187], v207 offset:36864
	ds_read_b128 v[188:191], v207 offset:37888
	ds_read_b128 v[192:195], v207 offset:38912
	ds_read_b128 v[198:201], v207 offset:39936
	global_load_lds_dwordx4 v[112:113], off
	v_lshl_add_u64 v[112:113], s[62:63], 0, v[144:145]
	s_mov_b32 m0, s74
	s_nop 0
	global_load_lds_dwordx4 v[112:113], off
	s_waitcnt lgkmcnt(8)
	s_barrier
	s_waitcnt lgkmcnt(0)
	s_waitcnt lgkmcnt(0)
	v_mfma_f32_16x16x32_bf16 v[138:141], v[96:99], v[162:165], v[138:141]
	v_mfma_f32_16x16x32_bf16 v[60:63], v[104:107], v[162:165], v[60:63]
	v_mfma_f32_16x16x32_bf16 v[134:137], v[96:99], v[170:173], v[134:137]
	v_mfma_f32_16x16x32_bf16 v[56:59], v[104:107], v[170:173], v[56:59]
	v_mfma_f32_16x16x32_bf16 v[130:133], v[96:99], v[184:187], v[130:133]
	v_mfma_f32_16x16x32_bf16 v[52:55], v[104:107], v[184:187], v[52:55]
	v_mfma_f32_16x16x32_bf16 v[126:129], v[96:99], v[192:195], v[126:129]
	v_mfma_f32_16x16x32_bf16 v[48:51], v[104:107], v[192:195], v[48:51]
	v_mfma_f32_16x16x32_bf16 v[138:141], v[100:103], v[166:169], v[138:141]
	v_mfma_f32_16x16x32_bf16 v[60:63], v[158:161], v[166:169], v[60:63]
	v_mfma_f32_16x16x32_bf16 v[134:137], v[100:103], v[180:183], v[134:137]
	v_mfma_f32_16x16x32_bf16 v[56:59], v[158:161], v[180:183], v[56:59]
	v_mfma_f32_16x16x32_bf16 v[130:133], v[100:103], v[188:191], v[130:133]
	v_mfma_f32_16x16x32_bf16 v[52:55], v[158:161], v[188:191], v[52:55]
	v_mfma_f32_16x16x32_bf16 v[126:129], v[100:103], v[198:201], v[126:129]
	v_mfma_f32_16x16x32_bf16 v[48:51], v[158:161], v[198:201], v[48:51]
	s_barrier
	s_add_i32 s35, 0, 0x1c000
	v_add_u32_e32 v112, s35, v196
	s_add_i32 s34, s34, s39
	ds_read_b128 v[208:211], v112
	ds_read_b128 v[212:215], v112 offset:1024
	ds_read_b128 v[216:219], v112 offset:2048
	ds_read_b128 v[220:223], v112 offset:3072
	v_lshl_add_u64 v[112:113], v[174:175], 0, s[40:41]
	s_mov_b32 m0, s34
	s_nop 0
	global_load_lds_dwordx4 v[112:113], off
	v_lshl_add_u64 v[112:113], v[224:225], 0, s[40:41]
	s_add_i32 m0, s34, 0x2000
	s_nop 0
	global_load_lds_dwordx4 v[112:113], off
	s_barrier
	s_waitcnt lgkmcnt(0)
	s_waitcnt lgkmcnt(0)
	v_mfma_f32_16x16x32_bf16 v[122:125], v[208:211], v[162:165], v[122:125]
	v_mfma_f32_16x16x32_bf16 v[44:47], v[216:219], v[162:165], v[44:47]
	v_mfma_f32_16x16x32_bf16 v[112:115], v[208:211], v[170:173], v[114:117]
	v_mfma_f32_16x16x32_bf16 v[36:39], v[216:219], v[170:173], v[36:39]
	v_mfma_f32_16x16x32_bf16 v[118:121], v[208:211], v[184:187], v[118:121]
	v_mfma_f32_16x16x32_bf16 v[40:43], v[216:219], v[184:187], v[40:43]
	v_mfma_f32_16x16x32_bf16 v[108:111], v[208:211], v[192:195], v[108:111]
	v_mfma_f32_16x16x32_bf16 v[32:35], v[216:219], v[192:195], v[32:35]
	v_mfma_f32_16x16x32_bf16 v[122:125], v[212:215], v[166:169], v[122:125]
	v_mfma_f32_16x16x32_bf16 v[44:47], v[220:223], v[166:169], v[44:47]
	v_mfma_f32_16x16x32_bf16 v[114:117], v[212:215], v[180:183], v[112:115]
	v_mfma_f32_16x16x32_bf16 v[36:39], v[220:223], v[180:183], v[36:39]
	v_mfma_f32_16x16x32_bf16 v[118:121], v[212:215], v[188:191], v[118:121]
	v_mfma_f32_16x16x32_bf16 v[40:43], v[220:223], v[188:191], v[40:43]
	v_mfma_f32_16x16x32_bf16 v[110:113], v[212:215], v[198:201], v[108:111]
	v_mfma_f32_16x16x32_bf16 v[32:35], v[220:223], v[198:201], v[32:35]
	s_mov_b32 m0, s76
	v_lshl_add_u64 v[108:109], v[226:227], 0, s[40:41]
	s_barrier
	ds_read_b128 v[162:165], v207 offset:49152
	ds_read_b128 v[166:169], v207 offset:50176
	ds_read_b128 v[170:173], v207 offset:51200
	ds_read_b128 v[180:183], v207 offset:52224
	ds_read_b128 v[184:187], v207 offset:53248
	ds_read_b128 v[188:191], v207 offset:54272
	ds_read_b128 v[192:195], v207 offset:55296
	ds_read_b128 v[198:201], v207 offset:56320
	global_load_lds_dwordx4 v[108:109], off
	v_lshl_add_u64 v[108:109], v[228:229], 0, s[40:41]
	s_mov_b32 m0, s77
	s_nop 0
	global_load_lds_dwordx4 v[108:109], off
	s_barrier
	s_waitcnt lgkmcnt(0)
	s_waitcnt lgkmcnt(0)
	v_mfma_f32_16x16x32_bf16 v[92:95], v[96:99], v[162:165], v[92:95]
	v_mfma_f32_16x16x32_bf16 v[28:31], v[104:107], v[162:165], v[28:31]
	v_mfma_f32_16x16x32_bf16 v[88:91], v[96:99], v[170:173], v[88:91]
	v_mfma_f32_16x16x32_bf16 v[24:27], v[104:107], v[170:173], v[24:27]
	v_mfma_f32_16x16x32_bf16 v[84:87], v[96:99], v[184:187], v[84:87]
	v_mfma_f32_16x16x32_bf16 v[20:23], v[104:107], v[184:187], v[20:23]
	v_mfma_f32_16x16x32_bf16 v[80:83], v[96:99], v[192:195], v[80:83]
	v_mfma_f32_16x16x32_bf16 v[16:19], v[104:107], v[192:195], v[16:19]
	v_mfma_f32_16x16x32_bf16 v[92:95], v[100:103], v[166:169], v[92:95]
	v_mfma_f32_16x16x32_bf16 v[28:31], v[158:161], v[166:169], v[28:31]
	v_mfma_f32_16x16x32_bf16 v[88:91], v[100:103], v[180:183], v[88:91]
	v_mfma_f32_16x16x32_bf16 v[24:27], v[158:161], v[180:183], v[24:27]
	v_mfma_f32_16x16x32_bf16 v[84:87], v[100:103], v[188:191], v[84:87]
	v_mfma_f32_16x16x32_bf16 v[20:23], v[158:161], v[188:191], v[20:23]
	v_mfma_f32_16x16x32_bf16 v[80:83], v[100:103], v[198:201], v[80:83]
	v_mfma_f32_16x16x32_bf16 v[16:19], v[158:161], v[198:201], v[16:19]
	s_barrier
	s_add_u32 s62, s66, 0x80080
	s_addc_u32 s63, s67, 0
	s_add_i32 s34, s35, s39
	v_lshl_add_u64 v[96:97], s[62:63], 0, v[146:147]
	s_mov_b32 m0, s34
	s_nop 0
	global_load_lds_dwordx4 v[96:97], off
	v_lshl_add_u64 v[96:97], s[62:63], 0, v[142:143]
	s_add_i32 m0, s34, 0x2000
	s_nop 0
	global_load_lds_dwordx4 v[96:97], off
	s_waitcnt vmcnt(6)
	s_barrier
	v_mfma_f32_16x16x32_bf16 v[76:79], v[208:211], v[162:165], v[76:79]
	v_mfma_f32_16x16x32_bf16 v[12:15], v[216:219], v[162:165], v[12:15]
	v_mfma_f32_16x16x32_bf16 v[68:71], v[208:211], v[170:173], v[68:71]
	v_mfma_f32_16x16x32_bf16 v[4:7], v[216:219], v[170:173], v[4:7]
	v_mfma_f32_16x16x32_bf16 v[72:75], v[208:211], v[184:187], v[72:75]
	v_mfma_f32_16x16x32_bf16 v[8:11], v[216:219], v[184:187], v[8:11]
	v_mfma_f32_16x16x32_bf16 v[64:67], v[208:211], v[192:195], v[64:67]
	v_mfma_f32_16x16x32_bf16 v[0:3], v[216:219], v[192:195], v[0:3]
	v_mfma_f32_16x16x32_bf16 v[76:79], v[212:215], v[166:169], v[76:79]
	v_mfma_f32_16x16x32_bf16 v[12:15], v[220:223], v[166:169], v[12:15]
	v_mfma_f32_16x16x32_bf16 v[68:71], v[212:215], v[180:183], v[68:71]
	v_mfma_f32_16x16x32_bf16 v[4:7], v[220:223], v[180:183], v[4:7]
	v_mfma_f32_16x16x32_bf16 v[72:75], v[212:215], v[188:191], v[72:75]
	v_mfma_f32_16x16x32_bf16 v[8:11], v[220:223], v[188:191], v[8:11]
	v_mfma_f32_16x16x32_bf16 v[64:67], v[212:215], v[198:201], v[64:67]
	v_mfma_f32_16x16x32_bf16 v[0:3], v[220:223], v[198:201], v[0:3]
	s_add_i32 s83, s83, 2
	s_add_u32 s81, s81, 0x100
	s_addc_u32 s82, s82, 0
	s_cmp_gt_u32 s83, 29
	s_mov_b64 s[62:63], s[64:65]
	s_barrier
	s_cbranch_scc0 .LBB0_173
	v_lshl_or_b32 v158, s70, 7, v150
	v_ashrrev_i32_e32 v159, 31, v158
	v_lshlrev_b64 v[96:97], 2, v[158:159]
	v_lshl_add_u64 v[98:99], s[30:31], 0, v[96:97]
	v_lshl_add_u64 v[100:101], s[46:47], 0, v[96:97]
	v_lshl_add_u64 v[102:103], s[24:25], 0, v[96:97]
	global_load_dwordx4 v[160:163], v[98:99], off
	global_load_dwordx4 v[170:173], v[100:101], off
	v_lshl_add_u64 v[98:99], s[42:43], 0, v[96:97]
	v_lshl_add_u64 v[100:101], s[48:49], 0, v[96:97]
	global_load_dwordx4 v[104:107], v[102:103], off
	global_load_dwordx4 v[164:167], v[98:99], off
	global_load_dwordx4 v[208:211], v[100:101], off
	v_lshl_add_u64 v[100:101], s[50:51], 0, v[96:97]
	global_load_dwordx4 v[212:215], v[100:101], off
	v_lshl_add_u64 v[98:99], s[26:27], 0, v[96:97]
	global_load_dwordx4 v[198:201], v[98:99], off
	v_lshl_add_u64 v[96:97], s[52:53], 0, v[96:97]
	global_load_dwordx4 v[216:219], v[96:97], off
	v_mov_b32_e32 v96, v177
	v_mov_b32_e32 v97, v177
	s_mov_b32 s62, 0xbf317218
	v_mov_b32_dpp v96, v126 row_ror:1 row_mask:0xf bank_mask:0xf
	v_mov_b32_dpp v97, v127 row_ror:1 row_mask:0xf bank_mask:0xf
	s_mov_b32 s34, 0xbfb8aa3b
	v_mov_b32_e32 v100, v177
	v_mov_b32_e32 v101, v177
	v_mov_b32_e32 v224, v177
	v_mov_b32_e32 v225, v177
	v_mov_b32_dpp v100, v138 row_ror:15 row_mask:0xf bank_mask:0xf
	v_mov_b32_dpp v101, v139 row_ror:15 row_mask:0xf bank_mask:0xf
	v_mov_b32_e32 v220, v177
	v_mov_b32_e32 v221, v177
	v_mov_b32_dpp v224, v112 row_ror:1 row_mask:0xf bank_mask:0xf
	v_mov_b32_dpp v225, v113 row_ror:1 row_mask:0xf bank_mask:0xf
	v_mov_b32_dpp v220, v128 row_ror:1 row_mask:0xf bank_mask:0xf
	v_mov_b32_dpp v221, v129 row_ror:1 row_mask:0xf bank_mask:0xf
	v_mov_b32_e32 v222, v177
	v_mov_b32_e32 v223, v177
	v_mov_b32_e32 v108, v177
	v_mov_b32_e32 v180, v177
	v_mov_b32_e32 v109, v177
	v_mov_b32_e32 v181, v177
	v_mov_b32_dpp v222, v140 row_ror:15 row_mask:0xf bank_mask:0xf
	v_mov_b32_dpp v223, v141 row_ror:15 row_mask:0xf bank_mask:0xf
	v_mov_b32_dpp v108, v110 row_ror:1 row_mask:0xf bank_mask:0xf
	v_mov_b32_dpp v180, v122 row_ror:15 row_mask:0xf bank_mask:0xf
	v_mov_b32_dpp v109, v111 row_ror:1 row_mask:0xf bank_mask:0xf
	v_mov_b32_dpp v181, v123 row_ror:15 row_mask:0xf bank_mask:0xf
	v_mov_b32_e32 v226, v177
	v_mov_b32_e32 v227, v177
	v_cmp_gt_i32_e32 vcc, 15, v151
	v_mov_b32_dpp v226, v124 row_ror:15 row_mask:0xf bank_mask:0xf
	v_mov_b32_dpp v227, v125 row_ror:15 row_mask:0xf bank_mask:0xf
	s_mov_b64 s[68:69], -1
	s_waitcnt vmcnt(0)
	v_pk_mul_f32 v[192:193], v[160:161], s[62:63] op_sel_hi:[1,0]
	v_pk_mul_f32 v[168:169], v[172:173], s[34:35] op_sel_hi:[1,0]
	v_pk_mul_f32 v[228:229], v[126:127], v[192:193]
	v_pk_mul_f32 v[194:195], v[162:163], s[62:63] op_sel_hi:[1,0]
	v_pk_mul_f32 v[186:187], v[104:105], s[62:63] op_sel_hi:[1,0]
	v_pk_mul_f32 v[188:189], v[166:167], s[62:63] op_sel_hi:[1,0]
	v_pk_mul_f32 v[172:173], v[210:211], s[34:35] op_sel_hi:[1,0]
	v_pk_mul_f32 v[96:97], v[186:187], v[96:97]
	v_pk_mul_f32 v[166:167], v[214:215], s[34:35] op_sel_hi:[1,0]
	v_pk_mul_f32 v[210:211], v[134:135], v[192:193]
	v_pk_mul_f32 v[214:215], v[130:131], v[192:193]
	v_pk_mul_f32 v[182:183], v[164:165], s[62:63] op_sel_hi:[1,0]
	v_pk_fma_f32 v[96:97], v[138:139], v[192:193], v[96:97]
	v_pk_fma_f32 v[210:211], v[138:139], v[186:187], v[210:211]
	v_pk_fma_f32 v[214:215], v[134:135], v[186:187], v[214:215]
	v_pk_fma_f32 v[228:229], v[130:131], v[186:187], v[228:229]
	v_pk_fma_f32 v[96:97], v[134:135], v[182:183], v[96:97]
	v_pk_fma_f32 v[210:211], v[130:131], v[182:183], v[210:211]
	v_pk_fma_f32 v[214:215], v[126:127], v[182:183], v[214:215]
	v_pk_fma_f32 v[100:101], v[182:183], v[100:101], v[228:229]
	v_pk_mul_f32 v[190:191], v[106:107], s[62:63] op_sel_hi:[1,0]
	v_pk_mul_f32 v[174:175], v[198:199], s[62:63] op_sel_hi:[1,0]
	v_pk_fma_f32 v[96:97], v[198:199], s[62:63], v[96:97] op_sel_hi:[1,0,1]
	v_pk_fma_f32 v[210:211], v[198:199], s[62:63], v[210:211] op_sel_hi:[1,0,1]
	v_pk_fma_f32 v[214:215], v[198:199], s[62:63], v[214:215] op_sel_hi:[1,0,1]
	v_pk_fma_f32 v[100:101], v[198:199], s[62:63], v[100:101] op_sel_hi:[1,0,1]
	v_pk_mul_f32 v[198:199], v[168:169], v[224:225]
	v_pk_mul_f32 v[164:165], v[170:171], s[34:35] op_sel_hi:[1,0]
	v_pk_mul_f32 v[170:171], v[208:209], s[34:35] op_sel_hi:[1,0]
	v_pk_mul_f32 v[162:163], v[212:213], s[34:35] op_sel_hi:[1,0]
	v_pk_mul_f32 v[104:105], v[190:191], v[220:221]
	v_pk_mul_f32 v[208:209], v[136:137], v[194:195]
	v_pk_mul_f32 v[212:213], v[132:133], v[194:195]
	v_pk_mul_f32 v[220:221], v[128:129], v[194:195]
	v_pk_fma_f32 v[198:199], v[124:125], v[172:173], v[198:199]
	v_pk_fma_f32 v[104:105], v[140:141], v[194:195], v[104:105]
	v_pk_fma_f32 v[208:209], v[140:141], v[190:191], v[208:209]
	v_pk_fma_f32 v[212:213], v[136:137], v[190:191], v[212:213]
	v_pk_fma_f32 v[220:221], v[132:133], v[190:191], v[220:221]
	v_pk_fma_f32 v[198:199], v[116:117], v[166:167], v[198:199]
	v_pk_mul_f32 v[232:233], v[110:111], v[170:171]
	v_pk_fma_f32 v[104:105], v[136:137], v[188:189], v[104:105]
	v_pk_fma_f32 v[208:209], v[132:133], v[188:189], v[208:209]
	v_pk_fma_f32 v[212:213], v[128:129], v[188:189], v[212:213]
	v_pk_fma_f32 v[220:221], v[188:189], v[222:223], v[220:221]
	v_pk_fma_f32 v[198:199], v[218:219], s[34:35], v[198:199] op_sel_hi:[1,0,1]
	v_pk_fma_f32 v[232:233], v[118:119], v[164:165], v[232:233]
	v_pk_mul_f32 v[184:185], v[200:201], s[62:63] op_sel_hi:[1,0]
	v_pk_fma_f32 v[104:105], v[200:201], s[62:63], v[104:105] op_sel_hi:[1,0,1]
	v_pk_fma_f32 v[208:209], v[200:201], s[62:63], v[208:209] op_sel_hi:[1,0,1]
	v_pk_fma_f32 v[212:213], v[200:201], s[62:63], v[212:213] op_sel_hi:[1,0,1]
	v_pk_fma_f32 v[200:201], v[200:201], s[62:63], v[220:221] op_sel_hi:[1,0,1]
	v_pk_mul_f32 v[108:109], v[164:165], v[108:109]
	v_pk_mul_f32 v[220:221], v[116:117], v[172:173]
	v_pk_mul_f32 v[222:223], v[114:115], v[170:171]
	v_pk_fma_f32 v[180:181], v[162:163], v[180:181], v[232:233]
	v_exp_f32_e32 v232, v198
	v_exp_f32_e32 v233, v199
	v_pk_fma_f32 v[108:109], v[122:123], v[170:171], v[108:109]
	v_pk_fma_f32 v[220:221], v[124:125], v[168:169], v[220:221]
	v_pk_fma_f32 v[222:223], v[122:123], v[164:165], v[222:223]
	v_pk_mul_f32 v[228:229], v[118:119], v[170:171]
	v_pk_fma_f32 v[108:109], v[114:115], v[162:163], v[108:109]
	v_pk_fma_f32 v[220:221], v[120:121], v[166:167], v[220:221]
	v_pk_fma_f32 v[222:223], v[118:119], v[162:163], v[222:223]
	v_pk_fma_f32 v[228:229], v[114:115], v[164:165], v[228:229]
	v_pk_mul_f32 v[230:231], v[112:113], v[172:173]
	v_pk_fma_f32 v[108:109], v[216:217], s[34:35], v[108:109] op_sel_hi:[1,0,1]
	v_pk_fma_f32 v[220:221], v[218:219], s[34:35], v[220:221] op_sel_hi:[1,0,1]
	v_pk_fma_f32 v[222:223], v[216:217], s[34:35], v[222:223] op_sel_hi:[1,0,1]
	v_pk_fma_f32 v[228:229], v[110:111], v[162:163], v[228:229]
	v_pk_fma_f32 v[230:231], v[120:121], v[168:169], v[230:231]
	v_pk_mul_f32 v[106:107], v[216:217], s[34:35] op_sel_hi:[1,0]
	v_pk_fma_f32 v[228:229], v[216:217], s[34:35], v[228:229] op_sel_hi:[1,0,1]
	v_pk_fma_f32 v[226:227], v[166:167], v[226:227], v[230:231]
	v_exp_f32_e32 v230, v108
	v_exp_f32_e32 v231, v109
	v_pk_fma_f32 v[180:181], v[216:217], s[34:35], v[180:181] op_sel_hi:[1,0,1]
	v_pk_add_f32 v[216:217], v[232:233], 1.0 op_sel_hi:[1,0]
	v_pk_mul_f32 v[104:105], v[104:105], v[198:199]
	v_pk_mul_f32 v[96:97], v[96:97], v[108:109]
	v_exp_f32_e32 v108, v222
	v_exp_f32_e32 v198, v220
	v_exp_f32_e32 v199, v221
	v_exp_f32_e32 v109, v223
	v_pk_mul_f32 v[224:225], v[120:121], v[172:173]
	v_rcp_f32_e32 v216, v216
	v_rcp_f32_e32 v217, v217
	v_pk_fma_f32 v[224:225], v[116:117], v[168:169], v[224:225]
	v_pk_add_f32 v[198:199], v[198:199], 1.0 op_sel_hi:[1,0]
	v_pk_fma_f32 v[224:225], v[112:113], v[166:167], v[224:225]
	v_pk_add_f32 v[108:109], v[108:109], 1.0 op_sel_hi:[1,0]
	v_pk_fma_f32 v[224:225], v[218:219], s[34:35], v[224:225] op_sel_hi:[1,0,1]
	v_pk_mul_f32 v[104:105], v[104:105], v[216:217]
	v_rcp_f32_e32 v108, v108
	v_rcp_f32_e32 v109, v109
	v_rcp_f32_e32 v198, v198
	v_rcp_f32_e32 v199, v199
	v_pk_mul_f32 v[208:209], v[208:209], v[220:221]
	v_exp_f32_e32 v216, v228
	v_exp_f32_e32 v220, v224
	v_exp_f32_e32 v221, v225
	v_exp_f32_e32 v217, v229
	v_pk_mul_f32 v[210:211], v[210:211], v[222:223]
	v_pk_mul_f32 v[160:161], v[218:219], s[34:35] op_sel_hi:[1,0]
	v_pk_fma_f32 v[218:219], v[218:219], s[34:35], v[226:227] op_sel_hi:[1,0,1]
	v_pk_mul_f32 v[198:199], v[208:209], v[198:199]
	v_pk_mul_f32 v[208:209], v[210:211], v[108:109]
	v_pk_add_f32 v[108:109], v[220:221], 1.0 op_sel_hi:[1,0]
	v_pk_add_f32 v[210:211], v[216:217], 1.0 op_sel_hi:[1,0]
	v_rcp_f32_e32 v108, v108
	v_rcp_f32_e32 v210, v210
	v_rcp_f32_e32 v211, v211
	v_rcp_f32_e32 v109, v109
	v_exp_f32_e32 v216, v180
	v_exp_f32_e32 v220, v218
	v_exp_f32_e32 v221, v219
	v_exp_f32_e32 v217, v181
	v_pk_add_f32 v[226:227], v[230:231], 1.0 op_sel_hi:[1,0]
	v_pk_mul_f32 v[212:213], v[212:213], v[224:225]
	v_pk_mul_f32 v[214:215], v[214:215], v[228:229]
	v_rcp_f32_e32 v226, v226
	v_rcp_f32_e32 v227, v227
	v_pk_mul_f32 v[212:213], v[212:213], v[108:109]
	v_pk_mul_f32 v[210:211], v[214:215], v[210:211]
	v_pk_add_f32 v[108:109], v[220:221], 1.0 op_sel_hi:[1,0]
	v_pk_add_f32 v[214:215], v[216:217], 1.0 op_sel_hi:[1,0]
	v_rcp_f32_e32 v108, v108
	v_rcp_f32_e32 v214, v214
	v_rcp_f32_e32 v109, v109
	v_rcp_f32_e32 v215, v215
	v_pk_mul_f32 v[96:97], v[96:97], v[226:227]
	v_pk_mul_f32 v[200:201], v[200:201], v[218:219]
	v_pk_mul_f32 v[100:101], v[100:101], v[180:181]
	v_pk_mul_f32 v[180:181], v[200:201], v[108:109]
	v_pk_mul_f32 v[200:201], v[100:101], v[214:215]
	v_cvt_pk_bf16_f32 v108, v96, v97
	v_cvt_pk_bf16_f32 v109, v104, v105
	v_cvt_pk_bf16_f32 v104, v208, v209
	v_cvt_pk_bf16_f32 v105, v198, v199
	v_cvt_pk_bf16_f32 v100, v210, v211
	v_cvt_pk_bf16_f32 v101, v212, v213
	s_nop 0
	v_cvt_pk_bf16_f32 v96, v200, v201
	v_cvt_pk_bf16_f32 v97, v180, v181
	s_and_saveexec_b64 s[62:63], vcc
	v_cmp_eq_u32_e32 vcc, 0, v151
	s_orn2_b64 s[68:69], vcc, exec
	s_or_b64 exec, exec, s[62:63]
	s_lshl_b32 s34, s79, 2
	s_lshl_b32 s62, s70, 8
	s_add_i32 s64, s34, s38
	s_ashr_i32 s63, s62, 31
	v_lshlrev_b32_e32 v176, 2, v150
	s_mov_b64 s[66:67], exec
	s_and_b64 s[68:69], s[66:67], s[68:69]
	v_mov_b32_e32 v198, 0xbf1f24be
	s_mov_b64 exec, s[68:69]
	s_cbranch_execz .LBB0_178
	s_ashr_i32 s65, s64, 31
	s_lshl_b64 s[68:69], s[64:65], 2
	v_or_b32_e32 v178, s68, v152
	v_mov_b64_e32 v[180:181], s[4:5]
	s_mov_b32 s29, 0xb000
	v_mad_u64_u32 v[180:181], s[70:71], v178, s29, v[180:181]
	v_mad_i32_i24 v181, s69, v204, v181
	v_lshl_add_u64 v[180:181], s[62:63], 2, v[180:181]
	v_lshl_add_u64 v[180:181], v[180:181], 0, v[176:177]
	v_cndmask_b32_e64 v133, v133, v141, s[8:9]
	v_cndmask_b32_e64 v132, v132, v140, s[8:9]
	v_cndmask_b32_e64 v131, v131, v139, s[8:9]
	v_cndmask_b32_e64 v130, v130, v138, s[8:9]
	v_cndmask_b32_e64 v118, v118, v122, s[8:9]
	v_cndmask_b32_e64 v121, v121, v125, s[8:9]
	v_cndmask_b32_e64 v120, v120, v124, s[8:9]
	v_cndmask_b32_e64 v119, v119, v123, s[8:9]
	global_store_dwordx4 v[180:181], v[130:133], off
	global_store_dwordx4 v[180:181], v[118:121], off offset:512
	v_cndmask_b32_e64 v125, v129, v137, s[8:9]
	v_cndmask_b32_e64 v124, v128, v136, s[8:9]
	v_add_co_u32_e32 v118, vcc, s29, v180
	v_cndmask_b32_e64 v123, v127, v135, s[8:9]
	v_cndmask_b32_e64 v122, v126, v134, s[8:9]
	v_addc_co_u32_e32 v119, vcc, 0, v181, vcc
	v_cndmask_b32_e64 v113, v113, v117, s[8:9]
	v_cndmask_b32_e64 v112, v112, v116, s[8:9]
	v_cndmask_b32_e64 v111, v111, v115, s[8:9]
	v_cndmask_b32_e64 v110, v110, v114, s[8:9]
	global_store_dwordx4 v[118:119], v[122:125], off
	global_store_dwordx4 v[118:119], v[110:113], off offset:512

.LBB0_264:
	s_add_i32 s61, s24, 2
	s_add_u32 s26, s8, 0x80
	s_addc_u32 s25, s9, 0
	s_add_i32 s29, 0, 0x10000
	v_add_u32_e32 v140, s29, v193
	ds_read_b128 v[128:131], v140
	ds_read_b128 v[132:135], v140 offset:1024
	ds_read_b128 v[136:139], v140 offset:2048
	ds_read_b128 v[140:143], v140 offset:3072
	s_cmp_eq_u32 s47, s24
	s_cselect_b32 s24, s20, s26
	s_cselect_b32 s25, s21, s25
	s_cselect_b32 s27, s11, s60
	s_cselect_b32 s26, s10, s59
	v_lshl_add_u64 v[180:181], s[8:9], 0, v[174:175]
	s_add_i32 m0, s33, 0xc000
	ds_read_b128 v[144:147], v195
	ds_read_b128 v[148:151], v195 offset:1024
	ds_read_b128 v[152:155], v195 offset:2048
	ds_read_b128 v[156:159], v195 offset:3072
	ds_read_b128 v[160:163], v195 offset:4096
	ds_read_b128 v[164:167], v195 offset:5120
	ds_read_b128 v[184:187], v195 offset:6144
	ds_read_b128 v[188:191], v195 offset:7168
	global_load_lds_dwordx4 v[180:181], off
	v_lshl_add_u64 v[180:181], s[8:9], 0, v[182:183]
	s_add_i32 m0, s33, 0xe000
	s_nop 0
	global_load_lds_dwordx4 v[180:181], off
	s_waitcnt lgkmcnt(8)
	s_barrier
	s_waitcnt lgkmcnt(0)
	s_waitcnt lgkmcnt(0)
	v_mfma_f32_16x16x32_bf16 v[124:127], v[128:131], v[144:147], v[124:127]
	v_mfma_f32_16x16x32_bf16 v[120:123], v[136:139], v[144:147], v[120:123]
	v_mfma_f32_16x16x32_bf16 v[108:111], v[128:131], v[152:155], v[108:111]
	v_mfma_f32_16x16x32_bf16 v[104:107], v[136:139], v[152:155], v[104:107]
	v_mfma_f32_16x16x32_bf16 v[92:95], v[128:131], v[160:163], v[92:95]
	v_mfma_f32_16x16x32_bf16 v[88:91], v[136:139], v[160:163], v[88:91]
	v_mfma_f32_16x16x32_bf16 v[76:79], v[128:131], v[184:187], v[76:79]
	v_mfma_f32_16x16x32_bf16 v[72:75], v[136:139], v[184:187], v[72:75]
	v_mfma_f32_16x16x32_bf16 v[124:127], v[132:135], v[148:151], v[124:127]
	v_mfma_f32_16x16x32_bf16 v[120:123], v[140:143], v[148:151], v[120:123]
	v_mfma_f32_16x16x32_bf16 v[108:111], v[132:135], v[156:159], v[108:111]
	v_mfma_f32_16x16x32_bf16 v[104:107], v[140:143], v[156:159], v[104:107]
	v_mfma_f32_16x16x32_bf16 v[92:95], v[132:135], v[164:167], v[92:95]
	v_mfma_f32_16x16x32_bf16 v[88:91], v[140:143], v[164:167], v[88:91]
	v_mfma_f32_16x16x32_bf16 v[76:79], v[132:135], v[188:191], v[76:79]
	v_mfma_f32_16x16x32_bf16 v[72:75], v[140:143], v[188:191], v[72:75]
	s_barrier
	s_add_i32 s34, 0, 0x14000
	s_add_i32 s29, s29, s31
	v_add_u32_e32 v178, s34, v193
	v_lshl_add_u64 v[180:181], s[26:27], 0, v[176:177]
	s_mov_b32 m0, s29
	ds_read_b128 v[196:199], v178
	ds_read_b128 v[208:211], v178 offset:1024
	ds_read_b128 v[212:215], v178 offset:2048
	ds_read_b128 v[216:219], v178 offset:3072
	global_load_lds_dwordx4 v[180:181], off
	v_lshl_add_u64 v[200:201], s[26:27], 0, v[168:169]
	s_add_i32 m0, s29, 0x2000
	s_nop 0
	global_load_lds_dwordx4 v[200:201], off
	s_barrier
	s_waitcnt lgkmcnt(0)
	s_waitcnt lgkmcnt(0)
	v_mfma_f32_16x16x32_bf16 v[116:119], v[196:199], v[144:147], v[116:119]
	v_mfma_f32_16x16x32_bf16 v[112:115], v[212:215], v[144:147], v[112:115]
	v_mfma_f32_16x16x32_bf16 v[100:103], v[196:199], v[152:155], v[100:103]
	v_mfma_f32_16x16x32_bf16 v[96:99], v[212:215], v[152:155], v[96:99]
	v_mfma_f32_16x16x32_bf16 v[84:87], v[196:199], v[160:163], v[84:87]
	v_mfma_f32_16x16x32_bf16 v[80:83], v[212:215], v[160:163], v[80:83]
	v_mfma_f32_16x16x32_bf16 v[68:71], v[196:199], v[184:187], v[68:71]
	v_mfma_f32_16x16x32_bf16 v[64:67], v[212:215], v[184:187], v[64:67]
	v_mfma_f32_16x16x32_bf16 v[116:119], v[208:211], v[148:151], v[116:119]
	v_mfma_f32_16x16x32_bf16 v[112:115], v[216:219], v[148:151], v[112:115]
	v_mfma_f32_16x16x32_bf16 v[100:103], v[208:211], v[156:159], v[100:103]
	v_mfma_f32_16x16x32_bf16 v[96:99], v[216:219], v[156:159], v[96:99]
	v_mfma_f32_16x16x32_bf16 v[84:87], v[208:211], v[164:167], v[84:87]
	v_mfma_f32_16x16x32_bf16 v[80:83], v[216:219], v[164:167], v[80:83]
	v_mfma_f32_16x16x32_bf16 v[68:71], v[208:211], v[188:191], v[68:71]
	v_mfma_f32_16x16x32_bf16 v[64:67], v[216:219], v[188:191], v[64:67]
	s_mov_b32 m0, s33
	v_lshl_add_u64 v[220:221], s[24:25], 0, v[172:173]
	s_barrier
	ds_read_b128 v[144:147], v195 offset:16384
	ds_read_b128 v[148:151], v195 offset:17408
	ds_read_b128 v[152:155], v195 offset:18432
	ds_read_b128 v[156:159], v195 offset:19456
	ds_read_b128 v[160:163], v195 offset:20480
	ds_read_b128 v[164:167], v195 offset:21504
	ds_read_b128 v[184:187], v195 offset:22528
	ds_read_b128 v[188:191], v195 offset:23552
	global_load_lds_dwordx4 v[220:221], off
	v_lshl_add_u64 v[222:223], s[24:25], 0, v[170:171]
	s_mov_b32 m0, s37
	s_nop 0
	global_load_lds_dwordx4 v[222:223], off
	s_barrier
	s_waitcnt lgkmcnt(0)
	s_waitcnt lgkmcnt(0)
	v_mfma_f32_16x16x32_bf16 v[60:63], v[128:131], v[144:147], v[60:63]
	v_mfma_f32_16x16x32_bf16 v[56:59], v[136:139], v[144:147], v[56:59]
	v_mfma_f32_16x16x32_bf16 v[44:47], v[128:131], v[152:155], v[44:47]
	v_mfma_f32_16x16x32_bf16 v[40:43], v[136:139], v[152:155], v[40:43]
	v_mfma_f32_16x16x32_bf16 v[28:31], v[128:131], v[160:163], v[28:31]
	v_mfma_f32_16x16x32_bf16 v[24:27], v[136:139], v[160:163], v[24:27]
	v_mfma_f32_16x16x32_bf16 v[12:15], v[128:131], v[184:187], v[12:15]
	v_mfma_f32_16x16x32_bf16 v[8:11], v[136:139], v[184:187], v[8:11]
	v_mfma_f32_16x16x32_bf16 v[60:63], v[132:135], v[148:151], v[60:63]
	v_mfma_f32_16x16x32_bf16 v[56:59], v[140:143], v[148:151], v[56:59]
	v_mfma_f32_16x16x32_bf16 v[44:47], v[132:135], v[156:159], v[44:47]
	v_mfma_f32_16x16x32_bf16 v[40:43], v[140:143], v[156:159], v[40:43]
	v_mfma_f32_16x16x32_bf16 v[28:31], v[132:135], v[164:167], v[28:31]
	v_mfma_f32_16x16x32_bf16 v[24:27], v[140:143], v[164:167], v[24:27]
	v_mfma_f32_16x16x32_bf16 v[12:15], v[132:135], v[188:191], v[12:15]
	v_mfma_f32_16x16x32_bf16 v[8:11], v[140:143], v[188:191], v[8:11]
	s_barrier
	s_add_u32 s26, s26, s44
	s_addc_u32 s27, s27, 0
	s_add_i32 s29, s34, s31
	v_lshl_add_u64 v[224:225], s[26:27], 0, v[176:177]
	s_mov_b32 m0, s29
	v_lshl_add_u64 v[226:227], s[26:27], 0, v[168:169]
	global_load_lds_dwordx4 v[224:225], off
	s_add_i32 m0, s29, 0x2000
	s_nop 0
	global_load_lds_dwordx4 v[226:227], off
	s_waitcnt vmcnt(6)
	s_barrier
	v_mfma_f32_16x16x32_bf16 v[52:55], v[196:199], v[144:147], v[52:55]
	v_mfma_f32_16x16x32_bf16 v[48:51], v[212:215], v[144:147], v[48:51]
	v_mfma_f32_16x16x32_bf16 v[36:39], v[196:199], v[152:155], v[36:39]
	v_mfma_f32_16x16x32_bf16 v[32:35], v[212:215], v[152:155], v[32:35]
	v_mfma_f32_16x16x32_bf16 v[20:23], v[196:199], v[160:163], v[20:23]
	v_mfma_f32_16x16x32_bf16 v[16:19], v[212:215], v[160:163], v[16:19]
	v_mfma_f32_16x16x32_bf16 v[4:7], v[196:199], v[184:187], v[4:7]
	v_mfma_f32_16x16x32_bf16 v[0:3], v[212:215], v[184:187], v[0:3]
	v_mfma_f32_16x16x32_bf16 v[52:55], v[208:211], v[148:151], v[52:55]
	v_mfma_f32_16x16x32_bf16 v[48:51], v[216:219], v[148:151], v[48:51]
	v_mfma_f32_16x16x32_bf16 v[36:39], v[208:211], v[156:159], v[36:39]
	v_mfma_f32_16x16x32_bf16 v[32:35], v[216:219], v[156:159], v[32:35]
	v_mfma_f32_16x16x32_bf16 v[20:23], v[208:211], v[164:167], v[20:23]
	v_mfma_f32_16x16x32_bf16 v[16:19], v[216:219], v[164:167], v[16:19]
	v_mfma_f32_16x16x32_bf16 v[4:7], v[208:211], v[188:191], v[4:7]
	v_mfma_f32_16x16x32_bf16 v[0:3], v[216:219], v[188:191], v[0:3]
	s_add_i32 s26, 0, 0x18000
	v_add_u32_e32 v140, s26, v193
	s_barrier
	ds_read_b128 v[128:131], v140
	ds_read_b128 v[132:135], v140 offset:1024
	ds_read_b128 v[136:139], v140 offset:2048
	ds_read_b128 v[140:143], v140 offset:3072
	s_add_u32 s24, s24, s44
	s_addc_u32 s25, s25, 0
	s_mov_b32 m0, s38
	v_lshl_add_u64 v[196:197], s[24:25], 0, v[172:173]
	ds_read_b128 v[144:147], v195 offset:32768
	ds_read_b128 v[148:151], v195 offset:33792
	ds_read_b128 v[152:155], v195 offset:34816
	ds_read_b128 v[156:159], v195 offset:35840
	ds_read_b128 v[160:163], v195 offset:36864
	ds_read_b128 v[164:167], v195 offset:37888
	ds_read_b128 v[184:187], v195 offset:38912
	ds_read_b128 v[188:191], v195 offset:39936
	global_load_lds_dwordx4 v[196:197], off
	v_lshl_add_u64 v[196:197], s[24:25], 0, v[170:171]
	s_mov_b32 m0, s39
	s_nop 0
	global_load_lds_dwordx4 v[196:197], off
	s_waitcnt lgkmcnt(8)
	s_barrier
	s_waitcnt lgkmcnt(0)
	s_waitcnt lgkmcnt(0)
	v_mfma_f32_16x16x32_bf16 v[124:127], v[128:131], v[144:147], v[124:127]
	v_mfma_f32_16x16x32_bf16 v[120:123], v[136:139], v[144:147], v[120:123]
	v_mfma_f32_16x16x32_bf16 v[108:111], v[128:131], v[152:155], v[108:111]
	v_mfma_f32_16x16x32_bf16 v[104:107], v[136:139], v[152:155], v[104:107]
	v_mfma_f32_16x16x32_bf16 v[92:95], v[128:131], v[160:163], v[92:95]
	v_mfma_f32_16x16x32_bf16 v[88:91], v[136:139], v[160:163], v[88:91]
	v_mfma_f32_16x16x32_bf16 v[76:79], v[128:131], v[184:187], v[76:79]
	v_mfma_f32_16x16x32_bf16 v[72:75], v[136:139], v[184:187], v[72:75]
	v_mfma_f32_16x16x32_bf16 v[124:127], v[132:135], v[148:151], v[124:127]
	v_mfma_f32_16x16x32_bf16 v[120:123], v[140:143], v[148:151], v[120:123]
	v_mfma_f32_16x16x32_bf16 v[108:111], v[132:135], v[156:159], v[108:111]
	v_mfma_f32_16x16x32_bf16 v[104:107], v[140:143], v[156:159], v[104:107]
	v_mfma_f32_16x16x32_bf16 v[92:95], v[132:135], v[164:167], v[92:95]
	v_mfma_f32_16x16x32_bf16 v[88:91], v[140:143], v[164:167], v[88:91]
	v_mfma_f32_16x16x32_bf16 v[76:79], v[132:135], v[188:191], v[76:79]
	v_mfma_f32_16x16x32_bf16 v[72:75], v[140:143], v[188:191], v[72:75]
	s_barrier
	s_add_i32 s24, 0, 0x1c000
	s_add_i32 s25, s26, s31
	v_add_u32_e32 v178, s24, v193
	v_lshl_add_u64 v[180:181], v[180:181], 0, s[40:41]
	s_mov_b32 m0, s25
	ds_read_b128 v[196:199], v178
	ds_read_b128 v[208:211], v178 offset:1024
	ds_read_b128 v[212:215], v178 offset:2048
	ds_read_b128 v[216:219], v178 offset:3072
	global_load_lds_dwordx4 v[180:181], off
	v_lshl_add_u64 v[180:181], v[200:201], 0, s[40:41]
	s_add_i32 m0, s25, 0x2000
	s_nop 0
	global_load_lds_dwordx4 v[180:181], off
	s_barrier
	s_waitcnt lgkmcnt(0)
	s_waitcnt lgkmcnt(0)
	v_mfma_f32_16x16x32_bf16 v[116:119], v[196:199], v[144:147], v[116:119]
	v_mfma_f32_16x16x32_bf16 v[112:115], v[212:215], v[144:147], v[112:115]
	v_mfma_f32_16x16x32_bf16 v[100:103], v[196:199], v[152:155], v[100:103]
	v_mfma_f32_16x16x32_bf16 v[96:99], v[212:215], v[152:155], v[96:99]
	v_mfma_f32_16x16x32_bf16 v[84:87], v[196:199], v[160:163], v[84:87]
	v_mfma_f32_16x16x32_bf16 v[80:83], v[212:215], v[160:163], v[80:83]
	v_mfma_f32_16x16x32_bf16 v[68:71], v[196:199], v[184:187], v[68:71]
	v_mfma_f32_16x16x32_bf16 v[64:67], v[212:215], v[184:187], v[64:67]
	v_mfma_f32_16x16x32_bf16 v[116:119], v[208:211], v[148:151], v[116:119]
	v_mfma_f32_16x16x32_bf16 v[112:115], v[216:219], v[148:151], v[112:115]
	v_mfma_f32_16x16x32_bf16 v[100:103], v[208:211], v[156:159], v[100:103]
	v_mfma_f32_16x16x32_bf16 v[96:99], v[216:219], v[156:159], v[96:99]
	v_mfma_f32_16x16x32_bf16 v[84:87], v[208:211], v[164:167], v[84:87]
	v_mfma_f32_16x16x32_bf16 v[80:83], v[216:219], v[164:167], v[80:83]
	v_mfma_f32_16x16x32_bf16 v[68:71], v[208:211], v[188:191], v[68:71]
	v_mfma_f32_16x16x32_bf16 v[64:67], v[216:219], v[188:191], v[64:67]
	s_mov_b32 m0, s43
	v_lshl_add_u64 v[180:181], v[220:221], 0, s[40:41]
	s_barrier
	ds_read_b128 v[144:147], v195 offset:49152
	ds_read_b128 v[148:151], v195 offset:50176
	ds_read_b128 v[152:155], v195 offset:51200
	ds_read_b128 v[156:159], v195 offset:52224
	ds_read_b128 v[160:163], v195 offset:53248
	ds_read_b128 v[164:167], v195 offset:54272
	ds_read_b128 v[184:187], v195 offset:55296
	ds_read_b128 v[188:191], v195 offset:56320
	global_load_lds_dwordx4 v[180:181], off
	v_lshl_add_u64 v[180:181], v[222:223], 0, s[40:41]
	s_mov_b32 m0, s46
	s_nop 0
	global_load_lds_dwordx4 v[180:181], off
	s_barrier
	s_waitcnt lgkmcnt(0)
	s_waitcnt lgkmcnt(0)
	v_mfma_f32_16x16x32_bf16 v[60:63], v[128:131], v[144:147], v[60:63]
	v_mfma_f32_16x16x32_bf16 v[56:59], v[136:139], v[144:147], v[56:59]
	v_mfma_f32_16x16x32_bf16 v[44:47], v[128:131], v[152:155], v[44:47]
	v_mfma_f32_16x16x32_bf16 v[40:43], v[136:139], v[152:155], v[40:43]
	v_mfma_f32_16x16x32_bf16 v[28:31], v[128:131], v[160:163], v[28:31]
	v_mfma_f32_16x16x32_bf16 v[24:27], v[136:139], v[160:163], v[24:27]
	v_mfma_f32_16x16x32_bf16 v[12:15], v[128:131], v[184:187], v[12:15]
	v_mfma_f32_16x16x32_bf16 v[8:11], v[136:139], v[184:187], v[8:11]
	v_mfma_f32_16x16x32_bf16 v[60:63], v[132:135], v[148:151], v[60:63]
	v_mfma_f32_16x16x32_bf16 v[56:59], v[140:143], v[148:151], v[56:59]
	v_mfma_f32_16x16x32_bf16 v[44:47], v[132:135], v[156:159], v[44:47]
	v_mfma_f32_16x16x32_bf16 v[40:43], v[140:143], v[156:159], v[40:43]
	v_mfma_f32_16x16x32_bf16 v[28:31], v[132:135], v[164:167], v[28:31]
	v_mfma_f32_16x16x32_bf16 v[24:27], v[140:143], v[164:167], v[24:27]
	v_mfma_f32_16x16x32_bf16 v[12:15], v[132:135], v[188:191], v[12:15]
	v_mfma_f32_16x16x32_bf16 v[8:11], v[140:143], v[188:191], v[8:11]
	s_barrier
	s_add_i32 s24, s24, s31
	v_lshl_add_u64 v[128:129], v[224:225], 0, s[40:41]
	s_mov_b32 m0, s24
	s_nop 0
	global_load_lds_dwordx4 v[128:129], off
	v_lshl_add_u64 v[128:129], v[226:227], 0, s[40:41]
	s_add_i32 m0, s24, 0x2000
	s_nop 0
	global_load_lds_dwordx4 v[128:129], off
	s_waitcnt vmcnt(6)
	s_barrier
	v_mfma_f32_16x16x32_bf16 v[52:55], v[196:199], v[144:147], v[52:55]
	v_mfma_f32_16x16x32_bf16 v[48:51], v[212:215], v[144:147], v[48:51]
	v_mfma_f32_16x16x32_bf16 v[36:39], v[196:199], v[152:155], v[36:39]
	v_mfma_f32_16x16x32_bf16 v[32:35], v[212:215], v[152:155], v[32:35]
	v_mfma_f32_16x16x32_bf16 v[20:23], v[196:199], v[160:163], v[20:23]
	v_mfma_f32_16x16x32_bf16 v[16:19], v[212:215], v[160:163], v[16:19]
	v_mfma_f32_16x16x32_bf16 v[4:7], v[196:199], v[184:187], v[4:7]
	v_mfma_f32_16x16x32_bf16 v[0:3], v[212:215], v[184:187], v[0:3]
	v_mfma_f32_16x16x32_bf16 v[52:55], v[208:211], v[148:151], v[52:55]
	v_mfma_f32_16x16x32_bf16 v[48:51], v[216:219], v[148:151], v[48:51]
	v_mfma_f32_16x16x32_bf16 v[36:39], v[208:211], v[156:159], v[36:39]
	v_mfma_f32_16x16x32_bf16 v[32:35], v[216:219], v[156:159], v[32:35]
	v_mfma_f32_16x16x32_bf16 v[20:23], v[208:211], v[164:167], v[20:23]
	v_mfma_f32_16x16x32_bf16 v[16:19], v[216:219], v[164:167], v[16:19]
	v_mfma_f32_16x16x32_bf16 v[4:7], v[208:211], v[188:191], v[4:7]
	v_mfma_f32_16x16x32_bf16 v[0:3], v[216:219], v[188:191], v[0:3]
	s_add_u32 s59, s59, 0x100
	s_addc_u32 s60, s60, 0
	s_add_u32 s8, s8, 0x100
	s_addc_u32 s9, s9, 0
	s_cmp_ge_u32 s61, s42
	s_mov_b32 s24, s61
	s_barrier
	s_cbranch_scc0 .LBB0_264
	s_sub_i32 s8, s57, 32
	s_lshr_b32 s8, s8, 3
	s_cmp_lt_i32 s57, 32
	s_cselect_b32 s26, 8, s8
	v_readlane_b32 s8, v255, 40
	v_readlane_b32 s9, v255, 41
	s_load_dwordx16 s[60:75], s[8:9], 0x0
	v_lshl_or_b32 v184, s58, 8, v194
	v_ashrrev_i32_e32 v185, 31, v184
	v_lshlrev_b64 v[128:129], 2, v[184:185]
	v_lshl_add_u32 v186, s57, 8, v192
	s_waitcnt lgkmcnt(0)
	s_cselect_b32 s24, s60, s50
	s_cselect_b32 s25, s61, s51
	s_add_i32 s8, s26, s53
	s_mul_hi_u32 s9, s8, 0xc000
	s_mul_i32 s8, s8, 0xc000
	s_add_u32 s8, s48, s8
	s_addc_u32 s9, s49, s9
	s_add_i32 s26, s54, s26
	s_mul_hi_u32 s27, s26, 0xc000
	s_mul_i32 s26, s26, 0xc000
	s_add_u32 s26, s48, s26
	s_addc_u32 s27, s49, s27
	v_lshl_add_u64 v[132:133], s[8:9], 0, v[128:129]
	v_lshl_add_u64 v[140:141], s[26:27], 0, v[128:129]
	global_load_dwordx4 v[144:147], v[132:133], off offset:16
	global_load_dwordx4 v[152:155], v[132:133], off
	global_load_dwordx4 v[148:151], v[140:141], off offset:16
	global_load_dwordx4 v[156:159], v[140:141], off
	global_load_dwordx4 v[128:131], v[132:133], off offset:528
	global_load_dwordx4 v[136:139], v[132:133], off offset:512
	s_nop 0
	global_load_dwordx4 v[132:135], v[140:141], off offset:528
	s_nop 0
	global_load_dwordx4 v[140:143], v[140:141], off offset:512
	v_lshl_add_u32 v196, v186, 11, v184
	v_lshlrev_b32_e32 v197, 2, v196
	v_lshlrev_b32_e32 v196, 1, v196
	s_and_b64 vcc, exec, s[4:5]
	s_cbranch_vccnz .Lres_f32
	global_load_dwordx4 v[164:167], v196, s[12:13]
	global_load_dwordx4 v[184:187], v196, s[12:13] offset:256
	s_add_u32 s62, s12, 0x10000
	s_addc_u32 s63, s13, 0
	global_load_dwordx4 v[188:191], v196, s[62:63]
	s_add_u32 s62, s12, 0x10000
	s_addc_u32 s63, s13, 0
	global_load_dwordx4 v[208:211], v196, s[62:63] offset:256
	s_add_u32 s62, s12, 0x20000
	s_addc_u32 s63, s13, 0
	global_load_dwordx4 v[212:215], v196, s[62:63]
	s_add_u32 s62, s12, 0x20000
	s_addc_u32 s63, s13, 0
	global_load_dwordx4 v[216:219], v196, s[62:63] offset:256
	s_add_u32 s62, s12, 0x30000
	s_addc_u32 s63, s13, 0
	global_load_dwordx4 v[220:223], v196, s[62:63]
	s_add_u32 s62, s12, 0x30000
	s_addc_u32 s63, s13, 0
	global_load_dwordx4 v[224:227], v196, s[62:63] offset:256
	s_waitcnt vmcnt(8)
	v_pk_add_f32 v[146:147], v[146:147], v[150:151]
	v_pk_add_f32 v[144:145], v[144:145], v[148:149]
	v_pk_add_f32 v[154:155], v[154:155], v[158:159]
	v_pk_add_f32 v[152:153], v[152:153], v[156:157]
	v_pk_add_f32 v[136:137], v[136:137], v[140:141]
	v_pk_add_f32 v[130:131], v[130:131], v[134:135]
	v_pk_add_f32 v[128:129], v[128:129], v[132:133]
	v_pk_add_f32 v[138:139], v[138:139], v[142:143]
	s_add_u32 s62, s12, 0x80000
	s_addc_u32 s63, s13, 0
	global_load_dwordx4 v[148:151], v196, s[62:63]
	s_add_u32 s62, s12, 0x80000
	s_addc_u32 s63, s13, 0
	global_load_dwordx4 v[156:159], v196, s[62:63] offset:256
	s_add_u32 s62, s12, 0x90000
	s_addc_u32 s63, s13, 0
	global_load_dwordx4 v[132:135], v196, s[62:63]
	s_add_u32 s62, s12, 0x90000
	s_addc_u32 s63, s13, 0
	global_load_dwordx4 v[140:143], v196, s[62:63] offset:256
	s_waitcnt vmcnt(11)
	v_lshlrev_b32_e32 v160, 16, v164
	v_and_b32_e32 v161, 0xffff0000, v164
	v_lshlrev_b32_e32 v162, 16, v165
	v_and_b32_e32 v163, 0xffff0000, v165
	v_lshlrev_b32_e32 v164, 16, v166
	v_and_b32_e32 v165, 0xffff0000, v166
	v_lshlrev_b32_e32 v166, 16, v167
	v_and_b32_e32 v167, 0xffff0000, v167
	v_pk_fma_f32 v[124:125], v[124:125], v[152:153], v[160:161]
	v_pk_fma_f32 v[126:127], v[126:127], v[154:155], v[162:163]
	v_pk_fma_f32 v[120:121], v[120:121], v[144:145], v[164:165]
	v_pk_fma_f32 v[122:123], v[122:123], v[146:147], v[166:167]
	s_add_u32 s62, s12, 0xa0000
	s_addc_u32 s63, s13, 0
	global_load_dwordx4 v[164:167], v196, s[62:63]
	v_cvt_pk_bf16_f32 v124, v124, v125
	v_cvt_pk_bf16_f32 v125, v126, v127
	v_cvt_pk_bf16_f32 v126, v120, v121
	v_cvt_pk_bf16_f32 v127, v122, v123
	global_store_dwordx4 v196, v[124:127], s[12:13]
	s_waitcnt vmcnt(12)
	v_lshlrev_b32_e32 v160, 16, v184
	v_and_b32_e32 v161, 0xffff0000, v184
	v_lshlrev_b32_e32 v162, 16, v185
	v_and_b32_e32 v163, 0xffff0000, v185
	v_lshlrev_b32_e32 v184, 16, v186
	v_and_b32_e32 v185, 0xffff0000, v186
	v_lshlrev_b32_e32 v186, 16, v187
	v_and_b32_e32 v187, 0xffff0000, v187
	v_pk_fma_f32 v[116:117], v[116:117], v[136:137], v[160:161]
	v_pk_fma_f32 v[118:119], v[118:119], v[138:139], v[162:163]
	v_pk_fma_f32 v[112:113], v[112:113], v[128:129], v[184:185]
	v_pk_fma_f32 v[114:115], v[114:115], v[130:131], v[186:187]
	s_add_u32 s62, s12, 0xa0000
	s_addc_u32 s63, s13, 0
	global_load_dwordx4 v[184:187], v196, s[62:63] offset:256
	v_cvt_pk_bf16_f32 v116, v116, v117
	v_cvt_pk_bf16_f32 v117, v118, v119
	v_cvt_pk_bf16_f32 v118, v112, v113
	v_cvt_pk_bf16_f32 v119, v114, v115
	global_store_dwordx4 v196, v[116:119], s[12:13] offset:256
	s_waitcnt vmcnt(13)
	v_lshlrev_b32_e32 v160, 16, v188
	v_and_b32_e32 v161, 0xffff0000, v188
	v_lshlrev_b32_e32 v162, 16, v189
	v_and_b32_e32 v163, 0xffff0000, v189
	v_lshlrev_b32_e32 v188, 16, v190
	v_and_b32_e32 v189, 0xffff0000, v190
	v_lshlrev_b32_e32 v190, 16, v191
	v_and_b32_e32 v191, 0xffff0000, v191
	v_pk_fma_f32 v[108:109], v[108:109], v[152:153], v[160:161]
	v_pk_fma_f32 v[110:111], v[110:111], v[154:155], v[162:163]
	v_pk_fma_f32 v[104:105], v[104:105], v[144:145], v[188:189]
	v_pk_fma_f32 v[106:107], v[106:107], v[146:147], v[190:191]
	s_add_u32 s62, s12, 0xb0000
	s_addc_u32 s63, s13, 0
	global_load_dwordx4 v[188:191], v196, s[62:63]
	v_cvt_pk_bf16_f32 v108, v108, v109
	v_cvt_pk_bf16_f32 v109, v110, v111
	v_cvt_pk_bf16_f32 v110, v104, v105
	v_cvt_pk_bf16_f32 v111, v106, v107
	s_add_u32 s64, s12, 0x10000
	s_addc_u32 s65, s13, 0
	global_store_dwordx4 v196, v[108:111], s[64:65]
	s_waitcnt vmcnt(14)
	v_lshlrev_b32_e32 v160, 16, v208
	v_and_b32_e32 v161, 0xffff0000, v208
	v_lshlrev_b32_e32 v162, 16, v209
	v_and_b32_e32 v163, 0xffff0000, v209
	v_lshlrev_b32_e32 v208, 16, v210
	v_and_b32_e32 v209, 0xffff0000, v210
	v_lshlrev_b32_e32 v210, 16, v211
	v_and_b32_e32 v211, 0xffff0000, v211
	v_pk_fma_f32 v[100:101], v[100:101], v[136:137], v[160:161]
	v_pk_fma_f32 v[102:103], v[102:103], v[138:139], v[162:163]
	v_pk_fma_f32 v[96:97], v[96:97], v[128:129], v[208:209]
	v_pk_fma_f32 v[98:99], v[98:99], v[130:131], v[210:211]
	s_add_u32 s62, s12, 0xb0000
	s_addc_u32 s63, s13, 0
	global_load_dwordx4 v[208:211], v196, s[62:63] offset:256
	v_cvt_pk_bf16_f32 v100, v100, v101
	v_cvt_pk_bf16_f32 v101, v102, v103
	v_cvt_pk_bf16_f32 v102, v96, v97
	v_cvt_pk_bf16_f32 v103, v98, v99
	s_add_u32 s64, s12, 0x10000
	s_addc_u32 s65, s13, 0
	global_store_dwordx4 v196, v[100:103], s[64:65] offset:256
	s_waitcnt vmcnt(15)
	v_lshlrev_b32_e32 v160, 16, v212
	v_and_b32_e32 v161, 0xffff0000, v212
	v_lshlrev_b32_e32 v162, 16, v213
	v_and_b32_e32 v163, 0xffff0000, v213
	v_lshlrev_b32_e32 v212, 16, v214
	v_and_b32_e32 v213, 0xffff0000, v214
	v_lshlrev_b32_e32 v214, 16, v215
	v_and_b32_e32 v215, 0xffff0000, v215
	v_pk_fma_f32 v[92:93], v[92:93], v[152:153], v[160:161]
	v_pk_fma_f32 v[94:95], v[94:95], v[154:155], v[162:163]
	v_pk_fma_f32 v[88:89], v[88:89], v[144:145], v[212:213]
	v_pk_fma_f32 v[90:91], v[90:91], v[146:147], v[214:215]
	v_cvt_pk_bf16_f32 v92, v92, v93
	v_cvt_pk_bf16_f32 v93, v94, v95
	v_cvt_pk_bf16_f32 v94, v88, v89
	v_cvt_pk_bf16_f32 v95, v90, v91
	s_add_u32 s64, s12, 0x20000
	s_addc_u32 s65, s13, 0
	global_store_dwordx4 v196, v[92:95], s[64:65]
	s_waitcnt vmcnt(15)
	v_lshlrev_b32_e32 v160, 16, v216
	v_and_b32_e32 v161, 0xffff0000, v216
	v_lshlrev_b32_e32 v162, 16, v217
	v_and_b32_e32 v163, 0xffff0000, v217
	v_lshlrev_b32_e32 v216, 16, v218
	v_and_b32_e32 v217, 0xffff0000, v218
	v_lshlrev_b32_e32 v218, 16, v219
	v_and_b32_e32 v219, 0xffff0000, v219
	v_pk_fma_f32 v[84:85], v[84:85], v[136:137], v[160:161]
	v_pk_fma_f32 v[86:87], v[86:87], v[138:139], v[162:163]
	v_pk_fma_f32 v[80:81], v[80:81], v[128:129], v[216:217]
	v_pk_fma_f32 v[82:83], v[82:83], v[130:131], v[218:219]
	v_cvt_pk_bf16_f32 v84, v84, v85
	v_cvt_pk_bf16_f32 v85, v86, v87
	v_cvt_pk_bf16_f32 v86, v80, v81
	v_cvt_pk_bf16_f32 v87, v82, v83
	s_add_u32 s64, s12, 0x20000
	s_addc_u32 s65, s13, 0
	global_store_dwordx4 v196, v[84:87], s[64:65] offset:256
	s_waitcnt vmcnt(15)
	v_lshlrev_b32_e32 v160, 16, v220
	v_and_b32_e32 v161, 0xffff0000, v220
	v_lshlrev_b32_e32 v162, 16, v221
	v_and_b32_e32 v163, 0xffff0000, v221
	v_lshlrev_b32_e32 v220, 16, v222
	v_and_b32_e32 v221, 0xffff0000, v222
	v_lshlrev_b32_e32 v222, 16, v223
	v_and_b32_e32 v223, 0xffff0000, v223
	v_pk_fma_f32 v[76:77], v[76:77], v[152:153], v[160:161]
	v_pk_fma_f32 v[78:79], v[78:79], v[154:155], v[162:163]
	v_pk_fma_f32 v[72:73], v[72:73], v[144:145], v[220:221]
	v_pk_fma_f32 v[74:75], v[74:75], v[146:147], v[222:223]
	v_cvt_pk_bf16_f32 v76, v76, v77
	v_cvt_pk_bf16_f32 v77, v78, v79
	v_cvt_pk_bf16_f32 v78, v72, v73
	v_cvt_pk_bf16_f32 v79, v74, v75
	s_add_u32 s64, s12, 0x30000
	s_addc_u32 s65, s13, 0
	global_store_dwordx4 v196, v[76:79], s[64:65]
	s_waitcnt vmcnt(15)
	v_lshlrev_b32_e32 v160, 16, v224
	v_and_b32_e32 v161, 0xffff0000, v224
	v_lshlrev_b32_e32 v162, 16, v225
	v_and_b32_e32 v163, 0xffff0000, v225
	v_lshlrev_b32_e32 v224, 16, v226
	v_and_b32_e32 v225, 0xffff0000, v226
	v_lshlrev_b32_e32 v226, 16, v227
	v_and_b32_e32 v227, 0xffff0000, v227
	v_pk_fma_f32 v[68:69], v[68:69], v[136:137], v[160:161]
	v_pk_fma_f32 v[70:71], v[70:71], v[138:139], v[162:163]
	v_pk_fma_f32 v[64:65], v[64:65], v[128:129], v[224:225]
	v_pk_fma_f32 v[66:67], v[66:67], v[130:131], v[226:227]
	v_cvt_pk_bf16_f32 v68, v68, v69
	v_cvt_pk_bf16_f32 v69, v70, v71
	v_cvt_pk_bf16_f32 v70, v64, v65
	v_cvt_pk_bf16_f32 v71, v66, v67
	s_add_u32 s64, s12, 0x30000
	s_addc_u32 s65, s13, 0
	global_store_dwordx4 v196, v[68:71], s[64:65] offset:256
	s_waitcnt vmcnt(15)
	v_lshlrev_b32_e32 v160, 16, v148
	v_and_b32_e32 v161, 0xffff0000, v148
	v_lshlrev_b32_e32 v162, 16, v149
	v_and_b32_e32 v163, 0xffff0000, v149
	v_lshlrev_b32_e32 v148, 16, v150
	v_and_b32_e32 v149, 0xffff0000, v150
	v_lshlrev_b32_e32 v150, 16, v151
	v_and_b32_e32 v151, 0xffff0000, v151
	v_pk_fma_f32 v[60:61], v[60:61], v[152:153], v[160:161]
	v_pk_fma_f32 v[62:63], v[62:63], v[154:155], v[162:163]
	v_pk_fma_f32 v[56:57], v[56:57], v[144:145], v[148:149]
	v_pk_fma_f32 v[58:59], v[58:59], v[146:147], v[150:151]
	v_cvt_pk_bf16_f32 v60, v60, v61
	v_cvt_pk_bf16_f32 v61, v62, v63
	v_cvt_pk_bf16_f32 v62, v56, v57
	v_cvt_pk_bf16_f32 v63, v58, v59
	s_add_u32 s64, s12, 0x80000
	s_addc_u32 s65, s13, 0
	global_store_dwordx4 v196, v[60:63], s[64:65]
	s_waitcnt vmcnt(15)
	v_lshlrev_b32_e32 v160, 16, v156
	v_and_b32_e32 v161, 0xffff0000, v156
	v_lshlrev_b32_e32 v162, 16, v157
	v_and_b32_e32 v163, 0xffff0000, v157
	v_lshlrev_b32_e32 v156, 16, v158
	v_and_b32_e32 v157, 0xffff0000, v158
	v_lshlrev_b32_e32 v158, 16, v159
	v_and_b32_e32 v159, 0xffff0000, v159
	v_pk_fma_f32 v[52:53], v[52:53], v[136:137], v[160:161]
	v_pk_fma_f32 v[54:55], v[54:55], v[138:139], v[162:163]
	v_pk_fma_f32 v[48:49], v[48:49], v[128:129], v[156:157]
	v_pk_fma_f32 v[50:51], v[50:51], v[130:131], v[158:159]
	v_cvt_pk_bf16_f32 v52, v52, v53
	v_cvt_pk_bf16_f32 v53, v54, v55
	v_cvt_pk_bf16_f32 v54, v48, v49
	v_cvt_pk_bf16_f32 v55, v50, v51
	s_add_u32 s64, s12, 0x80000
	s_addc_u32 s65, s13, 0
	global_store_dwordx4 v196, v[52:55], s[64:65] offset:256
	s_waitcnt vmcnt(15)
	v_lshlrev_b32_e32 v160, 16, v132
	v_and_b32_e32 v161, 0xffff0000, v132
	v_lshlrev_b32_e32 v162, 16, v133
	v_and_b32_e32 v163, 0xffff0000, v133
	v_lshlrev_b32_e32 v132, 16, v134
	v_and_b32_e32 v133, 0xffff0000, v134
	v_lshlrev_b32_e32 v134, 16, v135
	v_and_b32_e32 v135, 0xffff0000, v135
	v_pk_fma_f32 v[44:45], v[44:45], v[152:153], v[160:161]
	v_pk_fma_f32 v[46:47], v[46:47], v[154:155], v[162:163]
	v_pk_fma_f32 v[40:41], v[40:41], v[144:145], v[132:133]
	v_pk_fma_f32 v[42:43], v[42:43], v[146:147], v[134:135]
	v_cvt_pk_bf16_f32 v44, v44, v45
	v_cvt_pk_bf16_f32 v45, v46, v47
	v_cvt_pk_bf16_f32 v46, v40, v41
	v_cvt_pk_bf16_f32 v47, v42, v43
	s_add_u32 s64, s12, 0x90000
	s_addc_u32 s65, s13, 0
	global_store_dwordx4 v196, v[44:47], s[64:65]
	s_waitcnt vmcnt(15)
	v_lshlrev_b32_e32 v160, 16, v140
	v_and_b32_e32 v161, 0xffff0000, v140
	v_lshlrev_b32_e32 v162, 16, v141
	v_and_b32_e32 v163, 0xffff0000, v141
	v_lshlrev_b32_e32 v140, 16, v142
	v_and_b32_e32 v141, 0xffff0000, v142
	v_lshlrev_b32_e32 v142, 16, v143
	v_and_b32_e32 v143, 0xffff0000, v143
	v_pk_fma_f32 v[36:37], v[36:37], v[136:137], v[160:161]
	v_pk_fma_f32 v[38:39], v[38:39], v[138:139], v[162:163]
	v_pk_fma_f32 v[32:33], v[32:33], v[128:129], v[140:141]
	v_pk_fma_f32 v[34:35], v[34:35], v[130:131], v[142:143]
	v_cvt_pk_bf16_f32 v36, v36, v37
	v_cvt_pk_bf16_f32 v37, v38, v39
	v_cvt_pk_bf16_f32 v38, v32, v33
	v_cvt_pk_bf16_f32 v39, v34, v35
	s_add_u32 s64, s12, 0x90000
	s_addc_u32 s65, s13, 0
	global_store_dwordx4 v196, v[36:39], s[64:65] offset:256
	s_waitcnt vmcnt(15)
	v_lshlrev_b32_e32 v160, 16, v164
	v_and_b32_e32 v161, 0xffff0000, v164
	v_lshlrev_b32_e32 v162, 16, v165
	v_and_b32_e32 v163, 0xffff0000, v165
	v_lshlrev_b32_e32 v164, 16, v166
	v_and_b32_e32 v165, 0xffff0000, v166
	v_lshlrev_b32_e32 v166, 16, v167
	v_and_b32_e32 v167, 0xffff0000, v167
	v_pk_fma_f32 v[28:29], v[28:29], v[152:153], v[160:161]
	v_pk_fma_f32 v[30:31], v[30:31], v[154:155], v[162:163]
	v_pk_fma_f32 v[24:25], v[24:25], v[144:145], v[164:165]
	v_pk_fma_f32 v[26:27], v[26:27], v[146:147], v[166:167]
	v_cvt_pk_bf16_f32 v28, v28, v29
	v_cvt_pk_bf16_f32 v29, v30, v31
	v_cvt_pk_bf16_f32 v30, v24, v25
	v_cvt_pk_bf16_f32 v31, v26, v27
	s_add_u32 s64, s12, 0xa0000
	s_addc_u32 s65, s13, 0
	global_store_dwordx4 v196, v[28:31], s[64:65]
	s_waitcnt vmcnt(14)
	v_lshlrev_b32_e32 v160, 16, v184
	v_and_b32_e32 v161, 0xffff0000, v184
	v_lshlrev_b32_e32 v162, 16, v185
	v_and_b32_e32 v163, 0xffff0000, v185
	v_lshlrev_b32_e32 v184, 16, v186
	v_and_b32_e32 v185, 0xffff0000, v186
	v_lshlrev_b32_e32 v186, 16, v187
	v_and_b32_e32 v187, 0xffff0000, v187
	v_pk_fma_f32 v[20:21], v[20:21], v[136:137], v[160:161]
	v_pk_fma_f32 v[22:23], v[22:23], v[138:139], v[162:163]
	v_pk_fma_f32 v[16:17], v[16:17], v[128:129], v[184:185]
	v_pk_fma_f32 v[18:19], v[18:19], v[130:131], v[186:187]
	v_cvt_pk_bf16_f32 v20, v20, v21
	v_cvt_pk_bf16_f32 v21, v22, v23
	v_cvt_pk_bf16_f32 v22, v16, v17
	v_cvt_pk_bf16_f32 v23, v18, v19
	s_add_u32 s64, s12, 0xa0000
	s_addc_u32 s65, s13, 0
	global_store_dwordx4 v196, v[20:23], s[64:65] offset:256
	s_waitcnt vmcnt(13)
	v_lshlrev_b32_e32 v160, 16, v188
	v_and_b32_e32 v161, 0xffff0000, v188
	v_lshlrev_b32_e32 v162, 16, v189
	v_and_b32_e32 v163, 0xffff0000, v189
	v_lshlrev_b32_e32 v188, 16, v190
	v_and_b32_e32 v189, 0xffff0000, v190
	v_lshlrev_b32_e32 v190, 16, v191
	v_and_b32_e32 v191, 0xffff0000, v191
	v_pk_fma_f32 v[12:13], v[12:13], v[152:153], v[160:161]
	v_pk_fma_f32 v[14:15], v[14:15], v[154:155], v[162:163]
	v_pk_fma_f32 v[8:9], v[8:9], v[144:145], v[188:189]
	v_pk_fma_f32 v[10:11], v[10:11], v[146:147], v[190:191]
	v_cvt_pk_bf16_f32 v12, v12, v13
	v_cvt_pk_bf16_f32 v13, v14, v15
	v_cvt_pk_bf16_f32 v14, v8, v9
	v_cvt_pk_bf16_f32 v15, v10, v11
	s_add_u32 s64, s12, 0xb0000
	s_addc_u32 s65, s13, 0
	global_store_dwordx4 v196, v[12:15], s[64:65]
	s_waitcnt vmcnt(12)
	v_lshlrev_b32_e32 v160, 16, v208
	v_and_b32_e32 v161, 0xffff0000, v208
	v_lshlrev_b32_e32 v162, 16, v209
	v_and_b32_e32 v163, 0xffff0000, v209
	v_lshlrev_b32_e32 v208, 16, v210
	v_and_b32_e32 v209, 0xffff0000, v210
	v_lshlrev_b32_e32 v210, 16, v211
	v_and_b32_e32 v211, 0xffff0000, v211
	v_pk_fma_f32 v[4:5], v[4:5], v[136:137], v[160:161]
	v_pk_fma_f32 v[6:7], v[6:7], v[138:139], v[162:163]
	v_pk_fma_f32 v[0:1], v[0:1], v[128:129], v[208:209]
	v_pk_fma_f32 v[2:3], v[2:3], v[130:131], v[210:211]
	v_cvt_pk_bf16_f32 v4, v4, v5
	v_cvt_pk_bf16_f32 v5, v6, v7
	v_cvt_pk_bf16_f32 v6, v0, v1
	v_cvt_pk_bf16_f32 v7, v2, v3
	s_add_u32 s64, s12, 0xb0000
	s_addc_u32 s65, s13, 0
	global_store_dwordx4 v196, v[4:7], s[64:65] offset:256
	s_branch .Lres_done

.LBB0_639:
	s_add_i32 s60, s30, 2
	s_add_u32 s29, s26, 0x80
	s_addc_u32 s31, s27, 0
	s_add_i32 s34, 0, 0x10000
	v_add_u32_e32 v156, s34, v141
	ds_read_b128 v[144:147], v156
	ds_read_b128 v[148:151], v156 offset:1024
	ds_read_b128 v[152:155], v156 offset:2048
	ds_read_b128 v[156:159], v156 offset:3072
	s_cmp_eq_u32 s58, s30
	s_cselect_b32 s30, s20, s29
	s_cselect_b32 s31, s21, s31
	s_cselect_b32 s43, s25, s15
	s_cselect_b32 s42, s24, s13
	v_lshl_add_u64 v[196:197], s[26:27], 0, v[136:137]
	s_add_i32 m0, s17, 0xc000
	ds_read_b128 v[160:163], v143
	ds_read_b128 v[164:167], v143 offset:1024
	ds_read_b128 v[168:171], v143 offset:2048
	ds_read_b128 v[172:175], v143 offset:3072
	ds_read_b128 v[180:183], v143 offset:4096
	ds_read_b128 v[184:187], v143 offset:5120
	ds_read_b128 v[188:191], v143 offset:6144
	ds_read_b128 v[192:195], v143 offset:7168
	global_load_lds_dwordx4 v[196:197], off
	v_lshl_add_u64 v[196:197], s[26:27], 0, v[138:139]
	s_add_i32 m0, s17, 0xe000
	s_nop 0
	global_load_lds_dwordx4 v[196:197], off
	s_waitcnt lgkmcnt(8)
	s_barrier
	s_waitcnt lgkmcnt(0)
	s_waitcnt lgkmcnt(0)
	v_mfma_f32_16x16x32_bf16 v[124:127], v[144:147], v[160:163], v[124:127]
	v_mfma_f32_16x16x32_bf16 v[120:123], v[152:155], v[160:163], v[120:123]
	v_mfma_f32_16x16x32_bf16 v[116:119], v[144:147], v[168:171], v[116:119]
	v_mfma_f32_16x16x32_bf16 v[112:115], v[152:155], v[168:171], v[112:115]
	v_mfma_f32_16x16x32_bf16 v[108:111], v[144:147], v[180:183], v[108:111]
	v_mfma_f32_16x16x32_bf16 v[104:107], v[152:155], v[180:183], v[104:107]
	v_mfma_f32_16x16x32_bf16 v[100:103], v[144:147], v[188:191], v[100:103]
	v_mfma_f32_16x16x32_bf16 v[96:99], v[152:155], v[188:191], v[96:99]
	v_mfma_f32_16x16x32_bf16 v[124:127], v[148:151], v[164:167], v[124:127]
	v_mfma_f32_16x16x32_bf16 v[120:123], v[156:159], v[164:167], v[120:123]
	v_mfma_f32_16x16x32_bf16 v[116:119], v[148:151], v[172:175], v[116:119]
	v_mfma_f32_16x16x32_bf16 v[112:115], v[156:159], v[172:175], v[112:115]
	v_mfma_f32_16x16x32_bf16 v[108:111], v[148:151], v[184:187], v[108:111]
	v_mfma_f32_16x16x32_bf16 v[104:107], v[156:159], v[184:187], v[104:107]
	v_mfma_f32_16x16x32_bf16 v[100:103], v[148:151], v[192:195], v[100:103]
	v_mfma_f32_16x16x32_bf16 v[96:99], v[156:159], v[192:195], v[96:99]
	s_barrier
	s_add_i32 s29, 0, 0x14000
	s_add_i32 s34, s34, s48
	v_add_u32_e32 v176, s29, v141
	v_lshl_add_u64 v[200:201], s[42:43], 0, v[130:131]
	s_mov_b32 m0, s34
	ds_read_b128 v[196:199], v176
	ds_read_b128 v[208:211], v176 offset:1024
	ds_read_b128 v[212:215], v176 offset:2048
	ds_read_b128 v[216:219], v176 offset:3072
	global_load_lds_dwordx4 v[200:201], off
	v_lshl_add_u64 v[220:221], s[42:43], 0, v[134:135]
	s_add_i32 m0, s34, 0x2000
	s_nop 0
	global_load_lds_dwordx4 v[220:221], off
	s_barrier
	s_waitcnt lgkmcnt(0)
	s_waitcnt lgkmcnt(0)
	v_mfma_f32_16x16x32_bf16 v[72:75], v[196:199], v[160:163], v[72:75]
	v_mfma_f32_16x16x32_bf16 v[64:67], v[212:215], v[160:163], v[64:67]
	v_mfma_f32_16x16x32_bf16 v[56:59], v[196:199], v[168:171], v[56:59]
	v_mfma_f32_16x16x32_bf16 v[48:51], v[212:215], v[168:171], v[48:51]
	v_mfma_f32_16x16x32_bf16 v[44:47], v[196:199], v[180:183], v[44:47]
	v_mfma_f32_16x16x32_bf16 v[40:43], v[212:215], v[180:183], v[40:43]
	v_mfma_f32_16x16x32_bf16 v[36:39], v[196:199], v[188:191], v[36:39]
	v_mfma_f32_16x16x32_bf16 v[32:35], v[212:215], v[188:191], v[32:35]
	v_mfma_f32_16x16x32_bf16 v[72:75], v[208:211], v[164:167], v[72:75]
	v_mfma_f32_16x16x32_bf16 v[64:67], v[216:219], v[164:167], v[64:67]
	v_mfma_f32_16x16x32_bf16 v[56:59], v[208:211], v[172:175], v[56:59]
	v_mfma_f32_16x16x32_bf16 v[48:51], v[216:219], v[172:175], v[48:51]
	v_mfma_f32_16x16x32_bf16 v[44:47], v[208:211], v[184:187], v[44:47]
	v_mfma_f32_16x16x32_bf16 v[40:43], v[216:219], v[184:187], v[40:43]
	v_mfma_f32_16x16x32_bf16 v[36:39], v[208:211], v[192:195], v[36:39]
	v_mfma_f32_16x16x32_bf16 v[32:35], v[216:219], v[192:195], v[32:35]
	s_mov_b32 m0, s17
	v_lshl_add_u64 v[222:223], s[30:31], 0, v[128:129]
	s_barrier
	ds_read_b128 v[160:163], v143 offset:16384
	ds_read_b128 v[164:167], v143 offset:17408
	ds_read_b128 v[168:171], v143 offset:18432
	ds_read_b128 v[172:175], v143 offset:19456
	ds_read_b128 v[180:183], v143 offset:20480
	ds_read_b128 v[184:187], v143 offset:21504
	ds_read_b128 v[188:191], v143 offset:22528
	ds_read_b128 v[192:195], v143 offset:23552
	global_load_lds_dwordx4 v[222:223], off
	v_lshl_add_u64 v[224:225], s[30:31], 0, v[132:133]
	s_mov_b32 m0, s19
	s_nop 0
	global_load_lds_dwordx4 v[224:225], off
	s_barrier
	s_waitcnt lgkmcnt(0)
	s_waitcnt lgkmcnt(0)
	v_mfma_f32_16x16x32_bf16 v[92:95], v[144:147], v[160:163], v[92:95]
	v_mfma_f32_16x16x32_bf16 v[88:91], v[152:155], v[160:163], v[88:91]
	v_mfma_f32_16x16x32_bf16 v[84:87], v[144:147], v[168:171], v[84:87]
	v_mfma_f32_16x16x32_bf16 v[80:83], v[152:155], v[168:171], v[80:83]
	v_mfma_f32_16x16x32_bf16 v[76:79], v[144:147], v[180:183], v[76:79]
	v_mfma_f32_16x16x32_bf16 v[68:71], v[152:155], v[180:183], v[68:71]
	v_mfma_f32_16x16x32_bf16 v[60:63], v[144:147], v[188:191], v[60:63]
	v_mfma_f32_16x16x32_bf16 v[52:55], v[152:155], v[188:191], v[52:55]
	v_mfma_f32_16x16x32_bf16 v[92:95], v[148:151], v[164:167], v[92:95]
	v_mfma_f32_16x16x32_bf16 v[88:91], v[156:159], v[164:167], v[88:91]
	v_mfma_f32_16x16x32_bf16 v[84:87], v[148:151], v[172:175], v[84:87]
	v_mfma_f32_16x16x32_bf16 v[80:83], v[156:159], v[172:175], v[80:83]
	v_mfma_f32_16x16x32_bf16 v[76:79], v[148:151], v[184:187], v[76:79]
	v_mfma_f32_16x16x32_bf16 v[68:71], v[156:159], v[184:187], v[68:71]
	v_mfma_f32_16x16x32_bf16 v[60:63], v[148:151], v[192:195], v[60:63]
	v_mfma_f32_16x16x32_bf16 v[52:55], v[156:159], v[192:195], v[52:55]
	s_barrier
	s_add_u32 s34, s42, s44
	s_addc_u32 s35, s43, 0
	s_add_i32 s29, s29, s48
	v_lshl_add_u64 v[226:227], s[34:35], 0, v[130:131]
	s_mov_b32 m0, s29
	v_lshl_add_u64 v[228:229], s[34:35], 0, v[134:135]
	global_load_lds_dwordx4 v[226:227], off
	s_add_i32 m0, s29, 0x2000
	s_nop 0
	global_load_lds_dwordx4 v[228:229], off
	s_waitcnt vmcnt(6)
	s_barrier
	v_mfma_f32_16x16x32_bf16 v[28:31], v[196:199], v[160:163], v[28:31]
	v_mfma_f32_16x16x32_bf16 v[24:27], v[212:215], v[160:163], v[24:27]
	v_mfma_f32_16x16x32_bf16 v[20:23], v[196:199], v[168:171], v[20:23]
	v_mfma_f32_16x16x32_bf16 v[16:19], v[212:215], v[168:171], v[16:19]
	v_mfma_f32_16x16x32_bf16 v[12:15], v[196:199], v[180:183], v[12:15]
	v_mfma_f32_16x16x32_bf16 v[8:11], v[212:215], v[180:183], v[8:11]
	v_mfma_f32_16x16x32_bf16 v[4:7], v[196:199], v[188:191], v[4:7]
	v_mfma_f32_16x16x32_bf16 v[0:3], v[212:215], v[188:191], v[0:3]
	v_mfma_f32_16x16x32_bf16 v[28:31], v[208:211], v[164:167], v[28:31]
	v_mfma_f32_16x16x32_bf16 v[24:27], v[216:219], v[164:167], v[24:27]
	v_mfma_f32_16x16x32_bf16 v[20:23], v[208:211], v[172:175], v[20:23]
	v_mfma_f32_16x16x32_bf16 v[16:19], v[216:219], v[172:175], v[16:19]
	v_mfma_f32_16x16x32_bf16 v[12:15], v[208:211], v[184:187], v[12:15]
	v_mfma_f32_16x16x32_bf16 v[8:11], v[216:219], v[184:187], v[8:11]
	v_mfma_f32_16x16x32_bf16 v[4:7], v[208:211], v[192:195], v[4:7]
	v_mfma_f32_16x16x32_bf16 v[0:3], v[216:219], v[192:195], v[0:3]
	s_add_i32 s29, 0, 0x18000
	v_add_u32_e32 v156, s29, v141
	s_barrier
	ds_read_b128 v[144:147], v156
	ds_read_b128 v[148:151], v156 offset:1024
	ds_read_b128 v[152:155], v156 offset:2048
	ds_read_b128 v[156:159], v156 offset:3072
	s_add_u32 s30, s30, s44
	s_addc_u32 s31, s31, 0
	s_mov_b32 m0, s51
	v_lshl_add_u64 v[196:197], s[30:31], 0, v[128:129]
	ds_read_b128 v[160:163], v143 offset:32768
	ds_read_b128 v[164:167], v143 offset:33792
	ds_read_b128 v[168:171], v143 offset:34816
	ds_read_b128 v[172:175], v143 offset:35840
	ds_read_b128 v[180:183], v143 offset:36864
	ds_read_b128 v[184:187], v143 offset:37888
	ds_read_b128 v[188:191], v143 offset:38912
	ds_read_b128 v[192:195], v143 offset:39936
	global_load_lds_dwordx4 v[196:197], off
	v_lshl_add_u64 v[196:197], s[30:31], 0, v[132:133]
	s_mov_b32 m0, s52
	s_nop 0
	global_load_lds_dwordx4 v[196:197], off
	s_waitcnt lgkmcnt(8)
	s_barrier
	s_waitcnt lgkmcnt(0)
	s_waitcnt lgkmcnt(0)
	v_mfma_f32_16x16x32_bf16 v[124:127], v[144:147], v[160:163], v[124:127]
	v_mfma_f32_16x16x32_bf16 v[120:123], v[152:155], v[160:163], v[120:123]
	v_mfma_f32_16x16x32_bf16 v[116:119], v[144:147], v[168:171], v[116:119]
	v_mfma_f32_16x16x32_bf16 v[112:115], v[152:155], v[168:171], v[112:115]
	v_mfma_f32_16x16x32_bf16 v[108:111], v[144:147], v[180:183], v[108:111]
	v_mfma_f32_16x16x32_bf16 v[104:107], v[152:155], v[180:183], v[104:107]
	v_mfma_f32_16x16x32_bf16 v[100:103], v[144:147], v[188:191], v[100:103]
	v_mfma_f32_16x16x32_bf16 v[96:99], v[152:155], v[188:191], v[96:99]
	v_mfma_f32_16x16x32_bf16 v[124:127], v[148:151], v[164:167], v[124:127]
	v_mfma_f32_16x16x32_bf16 v[120:123], v[156:159], v[164:167], v[120:123]
	v_mfma_f32_16x16x32_bf16 v[116:119], v[148:151], v[172:175], v[116:119]
	v_mfma_f32_16x16x32_bf16 v[112:115], v[156:159], v[172:175], v[112:115]
	v_mfma_f32_16x16x32_bf16 v[108:111], v[148:151], v[184:187], v[108:111]
	v_mfma_f32_16x16x32_bf16 v[104:107], v[156:159], v[184:187], v[104:107]
	v_mfma_f32_16x16x32_bf16 v[100:103], v[148:151], v[192:195], v[100:103]
	v_mfma_f32_16x16x32_bf16 v[96:99], v[156:159], v[192:195], v[96:99]
	s_barrier
	s_add_i32 s30, 0, 0x1c000
	s_add_i32 s29, s29, s48
	v_add_u32_e32 v176, s30, v141
	v_lshl_add_u64 v[200:201], v[200:201], 0, s[40:41]
	s_mov_b32 m0, s29
	ds_read_b128 v[196:199], v176
	ds_read_b128 v[208:211], v176 offset:1024
	ds_read_b128 v[212:215], v176 offset:2048
	ds_read_b128 v[216:219], v176 offset:3072
	global_load_lds_dwordx4 v[200:201], off
	v_lshl_add_u64 v[200:201], v[220:221], 0, s[40:41]
	s_add_i32 m0, s29, 0x2000
	s_nop 0
	global_load_lds_dwordx4 v[200:201], off
	s_barrier
	s_waitcnt lgkmcnt(0)
	s_waitcnt lgkmcnt(0)
	v_mfma_f32_16x16x32_bf16 v[72:75], v[196:199], v[160:163], v[72:75]
	v_mfma_f32_16x16x32_bf16 v[64:67], v[212:215], v[160:163], v[64:67]
	v_mfma_f32_16x16x32_bf16 v[56:59], v[196:199], v[168:171], v[56:59]
	v_mfma_f32_16x16x32_bf16 v[48:51], v[212:215], v[168:171], v[48:51]
	v_mfma_f32_16x16x32_bf16 v[44:47], v[196:199], v[180:183], v[44:47]
	v_mfma_f32_16x16x32_bf16 v[40:43], v[212:215], v[180:183], v[40:43]
	v_mfma_f32_16x16x32_bf16 v[36:39], v[196:199], v[188:191], v[36:39]
	v_mfma_f32_16x16x32_bf16 v[32:35], v[212:215], v[188:191], v[32:35]
	v_mfma_f32_16x16x32_bf16 v[72:75], v[208:211], v[164:167], v[72:75]
	v_mfma_f32_16x16x32_bf16 v[64:67], v[216:219], v[164:167], v[64:67]
	v_mfma_f32_16x16x32_bf16 v[56:59], v[208:211], v[172:175], v[56:59]
	v_mfma_f32_16x16x32_bf16 v[48:51], v[216:219], v[172:175], v[48:51]
	v_mfma_f32_16x16x32_bf16 v[44:47], v[208:211], v[184:187], v[44:47]
	v_mfma_f32_16x16x32_bf16 v[40:43], v[216:219], v[184:187], v[40:43]
	v_mfma_f32_16x16x32_bf16 v[36:39], v[208:211], v[192:195], v[36:39]
	v_mfma_f32_16x16x32_bf16 v[32:35], v[216:219], v[192:195], v[32:35]
	s_mov_b32 m0, s56
	v_lshl_add_u64 v[200:201], v[222:223], 0, s[40:41]
	s_barrier
	ds_read_b128 v[160:163], v143 offset:49152
	ds_read_b128 v[164:167], v143 offset:50176
	ds_read_b128 v[168:171], v143 offset:51200
	ds_read_b128 v[172:175], v143 offset:52224
	ds_read_b128 v[180:183], v143 offset:53248
	ds_read_b128 v[184:187], v143 offset:54272
	ds_read_b128 v[188:191], v143 offset:55296
	ds_read_b128 v[192:195], v143 offset:56320
	global_load_lds_dwordx4 v[200:201], off
	v_lshl_add_u64 v[200:201], v[224:225], 0, s[40:41]
	s_mov_b32 m0, s57
	s_nop 0
	global_load_lds_dwordx4 v[200:201], off
	s_barrier
	s_waitcnt lgkmcnt(0)
	s_waitcnt lgkmcnt(0)
	v_mfma_f32_16x16x32_bf16 v[92:95], v[144:147], v[160:163], v[92:95]
	v_mfma_f32_16x16x32_bf16 v[88:91], v[152:155], v[160:163], v[88:91]
	v_mfma_f32_16x16x32_bf16 v[84:87], v[144:147], v[168:171], v[84:87]
	v_mfma_f32_16x16x32_bf16 v[80:83], v[152:155], v[168:171], v[80:83]
	v_mfma_f32_16x16x32_bf16 v[76:79], v[144:147], v[180:183], v[76:79]
	v_mfma_f32_16x16x32_bf16 v[68:71], v[152:155], v[180:183], v[68:71]
	v_mfma_f32_16x16x32_bf16 v[60:63], v[144:147], v[188:191], v[60:63]
	v_mfma_f32_16x16x32_bf16 v[52:55], v[152:155], v[188:191], v[52:55]
	v_mfma_f32_16x16x32_bf16 v[92:95], v[148:151], v[164:167], v[92:95]
	v_mfma_f32_16x16x32_bf16 v[88:91], v[156:159], v[164:167], v[88:91]
	v_mfma_f32_16x16x32_bf16 v[84:87], v[148:151], v[172:175], v[84:87]
	v_mfma_f32_16x16x32_bf16 v[80:83], v[156:159], v[172:175], v[80:83]
	v_mfma_f32_16x16x32_bf16 v[76:79], v[148:151], v[184:187], v[76:79]
	v_mfma_f32_16x16x32_bf16 v[68:71], v[156:159], v[184:187], v[68:71]
	v_mfma_f32_16x16x32_bf16 v[60:63], v[148:151], v[192:195], v[60:63]
	v_mfma_f32_16x16x32_bf16 v[52:55], v[156:159], v[192:195], v[52:55]
	s_barrier
	s_add_i32 s29, s30, s48
	v_lshl_add_u64 v[144:145], v[226:227], 0, s[40:41]
	s_mov_b32 m0, s29
	s_nop 0
	global_load_lds_dwordx4 v[144:145], off
	v_lshl_add_u64 v[144:145], v[228:229], 0, s[40:41]
	s_add_i32 m0, s29, 0x2000
	s_nop 0
	global_load_lds_dwordx4 v[144:145], off
	s_waitcnt vmcnt(6)
	s_barrier
	v_mfma_f32_16x16x32_bf16 v[28:31], v[196:199], v[160:163], v[28:31]
	v_mfma_f32_16x16x32_bf16 v[24:27], v[212:215], v[160:163], v[24:27]
	v_mfma_f32_16x16x32_bf16 v[20:23], v[196:199], v[168:171], v[20:23]
	v_mfma_f32_16x16x32_bf16 v[16:19], v[212:215], v[168:171], v[16:19]
	v_mfma_f32_16x16x32_bf16 v[12:15], v[196:199], v[180:183], v[12:15]
	v_mfma_f32_16x16x32_bf16 v[8:11], v[212:215], v[180:183], v[8:11]
	v_mfma_f32_16x16x32_bf16 v[4:7], v[196:199], v[188:191], v[4:7]
	v_mfma_f32_16x16x32_bf16 v[0:3], v[212:215], v[188:191], v[0:3]
	v_mfma_f32_16x16x32_bf16 v[28:31], v[208:211], v[164:167], v[28:31]
	v_mfma_f32_16x16x32_bf16 v[24:27], v[216:219], v[164:167], v[24:27]
	v_mfma_f32_16x16x32_bf16 v[20:23], v[208:211], v[172:175], v[20:23]
	v_mfma_f32_16x16x32_bf16 v[16:19], v[216:219], v[172:175], v[16:19]
	v_mfma_f32_16x16x32_bf16 v[12:15], v[208:211], v[184:187], v[12:15]
	v_mfma_f32_16x16x32_bf16 v[8:11], v[216:219], v[184:187], v[8:11]
	v_mfma_f32_16x16x32_bf16 v[4:7], v[208:211], v[192:195], v[4:7]
	v_mfma_f32_16x16x32_bf16 v[0:3], v[216:219], v[192:195], v[0:3]
	s_add_u32 s26, s26, 0x100
	s_addc_u32 s27, s27, 0
	s_add_u32 s13, s13, 0x100
	s_addc_u32 s15, s15, 0
	s_cmp_ge_u32 s60, s55
	s_mov_b32 s30, s60
	s_barrier
	s_cbranch_scc0 .LBB0_639
	s_lshl_b32 s13, s16, 8
	s_ashr_i32 s15, s16, 1
	s_and_b32 s13, s13, 0x100
	v_or_b32_e32 v145, s13, v142
	s_lshl_b32 s13, s15, s59
	s_add_i32 s26, s13, s54
	s_ashr_i32 s27, s26, 31
	s_lshl_b64 s[26:27], s[26:27], 12
	v_readlane_b32 s30, v255, 26
	v_lshl_add_u32 v144, s18, 8, v140
	v_readlane_b32 s31, v255, 27
	s_add_u32 s26, s30, s26
	s_addc_u32 s27, s31, s27
	v_lshlrev_b32_e32 v176, 1, v145
	v_pk_mul_f32 v[124:125], s[8:9], v[124:125]
	v_ashrrev_i32_e32 v145, 31, v144
	v_lshl_add_u64 v[146:147], s[26:27], 0, v[176:177]
	v_pk_mul_f32 v[148:149], s[10:11], v[122:123]
	v_pk_mul_f32 v[122:123], s[8:9], v[120:121]
	v_cvt_pk_bf16_f32 v120, v124, v125
	v_lshlrev_b64 v[124:125], 12, v[144:145]
	v_pk_mul_f32 v[126:127], s[10:11], v[126:127]
	v_lshl_add_u64 v[124:125], v[146:147], 0, v[124:125]
	v_cvt_pk_bf16_f32 v121, v126, v127
	v_pk_mul_f32 v[116:117], s[8:9], v[116:117]
	v_cvt_pk_bf16_f32 v122, v122, v123
	v_cvt_pk_bf16_f32 v123, v148, v149
	global_store_dwordx4 v[124:125], v[120:123], off offset:3072
	v_pk_mul_f32 v[118:119], s[10:11], v[118:119]
	v_pk_mul_f32 v[108:109], s[8:9], v[108:109]
	v_pk_mul_f32 v[120:121], s[10:11], v[114:115]
	v_pk_mul_f32 v[114:115], s[8:9], v[112:113]
	v_cvt_pk_bf16_f32 v112, v116, v117
	v_or_b32_e32 v116, 16, v144
	v_ashrrev_i32_e32 v117, 31, v116
	v_lshlrev_b64 v[116:117], 12, v[116:117]
	v_cvt_pk_bf16_f32 v113, v118, v119
	v_lshl_add_u64 v[116:117], v[146:147], 0, v[116:117]
	v_cvt_pk_bf16_f32 v114, v114, v115
	v_cvt_pk_bf16_f32 v115, v120, v121
	global_store_dwordx4 v[116:117], v[112:115], off offset:3072
	v_pk_mul_f32 v[110:111], s[10:11], v[110:111]
	v_pk_mul_f32 v[100:101], s[8:9], v[100:101]
	v_pk_mul_f32 v[112:113], s[10:11], v[106:107]
	v_pk_mul_f32 v[106:107], s[8:9], v[104:105]
	v_cvt_pk_bf16_f32 v104, v108, v109
	v_or_b32_e32 v108, 32, v144
	v_ashrrev_i32_e32 v109, 31, v108
	v_lshlrev_b64 v[108:109], 12, v[108:109]
	v_cvt_pk_bf16_f32 v105, v110, v111
	v_lshl_add_u64 v[108:109], v[146:147], 0, v[108:109]
	v_cvt_pk_bf16_f32 v106, v106, v107
	v_cvt_pk_bf16_f32 v107, v112, v113
	global_store_dwordx4 v[108:109], v[104:107], off offset:3072
	v_pk_mul_f32 v[102:103], s[10:11], v[102:103]
	v_pk_mul_f32 v[92:93], s[8:9], v[92:93]
	v_pk_mul_f32 v[104:105], s[10:11], v[98:99]
	v_pk_mul_f32 v[98:99], s[8:9], v[96:97]
	v_cvt_pk_bf16_f32 v96, v100, v101
	v_or_b32_e32 v100, 48, v144
	v_ashrrev_i32_e32 v101, 31, v100
	v_lshlrev_b64 v[100:101], 12, v[100:101]
	v_cvt_pk_bf16_f32 v97, v102, v103
	v_lshl_add_u64 v[100:101], v[146:147], 0, v[100:101]
	s_mov_b64 s[26:27], 0x80000
	v_cvt_pk_bf16_f32 v98, v98, v99
	v_cvt_pk_bf16_f32 v99, v104, v105
	global_store_dwordx4 v[100:101], v[96:99], off offset:3072
	v_pk_mul_f32 v[94:95], s[10:11], v[94:95]
	v_pk_mul_f32 v[84:85], s[8:9], v[84:85]
	v_pk_mul_f32 v[96:97], s[10:11], v[90:91]
	v_pk_mul_f32 v[90:91], s[8:9], v[88:89]
	v_cvt_pk_bf16_f32 v88, v92, v93
	v_cvt_pk_bf16_f32 v89, v94, v95
	v_lshl_add_u64 v[92:93], v[124:125], 0, s[26:27]
	s_mov_b64 s[26:27], 0x90000
	v_cvt_pk_bf16_f32 v90, v90, v91
	v_cvt_pk_bf16_f32 v91, v96, v97
	global_store_dwordx4 v[92:93], v[88:91], off offset:3072
	v_pk_mul_f32 v[86:87], s[10:11], v[86:87]
	v_pk_mul_f32 v[76:77], s[8:9], v[76:77]
	v_pk_mul_f32 v[88:89], s[10:11], v[82:83]
	v_pk_mul_f32 v[82:83], s[8:9], v[80:81]
	v_cvt_pk_bf16_f32 v80, v84, v85
	v_cvt_pk_bf16_f32 v81, v86, v87
	v_lshl_add_u64 v[84:85], v[124:125], 0, s[26:27]
	s_mov_b64 s[26:27], 0xa0000
	v_cvt_pk_bf16_f32 v82, v82, v83
	v_cvt_pk_bf16_f32 v83, v88, v89
	global_store_dwordx4 v[84:85], v[80:83], off offset:3072
	v_pk_mul_f32 v[78:79], s[10:11], v[78:79]
	v_pk_mul_f32 v[60:61], s[8:9], v[60:61]
	v_pk_mul_f32 v[80:81], s[10:11], v[70:71]
	v_pk_mul_f32 v[70:71], s[8:9], v[68:69]
	v_cvt_pk_bf16_f32 v68, v76, v77
	v_cvt_pk_bf16_f32 v69, v78, v79
	v_lshl_add_u64 v[76:77], v[124:125], 0, s[26:27]
	v_cvt_pk_bf16_f32 v70, v70, v71
	v_cvt_pk_bf16_f32 v71, v80, v81
	global_store_dwordx4 v[76:77], v[68:71], off offset:3072
	s_mov_b64 s[26:27], 0xb0000
	v_pk_mul_f32 v[62:63], s[10:11], v[62:63]
	v_pk_mul_f32 v[68:69], s[10:11], v[54:55]
	v_pk_mul_f32 v[54:55], s[8:9], v[52:53]
	v_cvt_pk_bf16_f32 v52, v60, v61
	v_cvt_pk_bf16_f32 v53, v62, v63
	v_lshl_add_u64 v[60:61], v[124:125], 0, s[26:27]
	v_cvt_pk_bf16_f32 v54, v54, v55
	v_cvt_pk_bf16_f32 v55, v68, v69
	global_store_dwordx4 v[60:61], v[52:55], off offset:3072
	v_pk_mul_f32 v[62:63], s[10:11], v[66:67]
	v_pk_mul_f32 v[64:65], s[8:9], v[64:65]
	v_pk_mul_f32 v[54:55], s[10:11], v[74:75]
	v_pk_mul_f32 v[52:53], s[8:9], v[72:73]
	v_pk_mul_f32 v[46:47], s[10:11], v[46:47]
	v_cvt_pk_bf16_f32 v52, v52, v53
	v_cvt_pk_bf16_f32 v53, v54, v55
	v_cvt_pk_bf16_f32 v54, v64, v65
	v_cvt_pk_bf16_f32 v55, v62, v63
	global_store_dwordx4 v[124:125], v[52:55], off offset:3328
	v_pk_mul_f32 v[44:45], s[8:9], v[44:45]
	v_pk_mul_f32 v[38:39], s[10:11], v[38:39]
	v_pk_mul_f32 v[52:53], s[10:11], v[58:59]
	v_pk_mul_f32 v[54:55], s[8:9], v[56:57]
	v_pk_mul_f32 v[56:57], s[10:11], v[50:51]
	v_pk_mul_f32 v[50:51], s[8:9], v[48:49]
	v_cvt_pk_bf16_f32 v48, v54, v55
	v_cvt_pk_bf16_f32 v49, v52, v53
	v_pk_mul_f32 v[36:37], s[8:9], v[36:37]
	v_cvt_pk_bf16_f32 v50, v50, v51
	v_cvt_pk_bf16_f32 v51, v56, v57
	global_store_dwordx4 v[116:117], v[48:51], off offset:3328
	v_pk_mul_f32 v[30:31], s[10:11], v[30:31]
	v_pk_mul_f32 v[28:29], s[8:9], v[28:29]
	v_pk_mul_f32 v[48:49], s[10:11], v[42:43]
	v_pk_mul_f32 v[42:43], s[8:9], v[40:41]
	v_cvt_pk_bf16_f32 v40, v44, v45
	v_cvt_pk_bf16_f32 v41, v46, v47
	v_pk_mul_f32 v[22:23], s[10:11], v[22:23]
	v_cvt_pk_bf16_f32 v42, v42, v43
	v_cvt_pk_bf16_f32 v43, v48, v49
	global_store_dwordx4 v[108:109], v[40:43], off offset:3328
	v_pk_mul_f32 v[20:21], s[8:9], v[20:21]
	v_pk_mul_f32 v[14:15], s[10:11], v[14:15]
	v_pk_mul_f32 v[40:41], s[10:11], v[34:35]
	v_pk_mul_f32 v[34:35], s[8:9], v[32:33]
	v_cvt_pk_bf16_f32 v32, v36, v37
	v_cvt_pk_bf16_f32 v33, v38, v39
	v_pk_mul_f32 v[12:13], s[8:9], v[12:13]
	v_cvt_pk_bf16_f32 v34, v34, v35
	v_cvt_pk_bf16_f32 v35, v40, v41
	global_store_dwordx4 v[100:101], v[32:35], off offset:3328
	s_and_b64 vcc, exec, s[6:7]
	s_mov_b32 s16, s12
	v_pk_mul_f32 v[32:33], s[10:11], v[26:27]
	v_pk_mul_f32 v[26:27], s[8:9], v[24:25]
	v_cvt_pk_bf16_f32 v24, v28, v29
	v_cvt_pk_bf16_f32 v25, v30, v31
	s_mov_b32 s18, s14
	v_cvt_pk_bf16_f32 v26, v26, v27
	v_cvt_pk_bf16_f32 v27, v32, v33
	global_store_dwordx4 v[92:93], v[24:27], off offset:3328
	s_mov_b64 s[30:31], s[24:25]
	s_mov_b64 s[26:27], s[20:21]
	v_pk_mul_f32 v[24:25], s[10:11], v[18:19]
	v_pk_mul_f32 v[18:19], s[8:9], v[16:17]
	v_cvt_pk_bf16_f32 v16, v20, v21
	v_cvt_pk_bf16_f32 v17, v22, v23
	v_pk_mul_f32 v[6:7], s[10:11], v[6:7]
	v_cvt_pk_bf16_f32 v18, v18, v19
	v_cvt_pk_bf16_f32 v19, v24, v25
	global_store_dwordx4 v[84:85], v[16:19], off offset:3328
	v_pk_mul_f32 v[4:5], s[8:9], v[4:5]
	s_nop 0
	v_pk_mul_f32 v[16:17], s[10:11], v[10:11]
	v_pk_mul_f32 v[10:11], s[8:9], v[8:9]
	v_cvt_pk_bf16_f32 v8, v12, v13
	v_cvt_pk_bf16_f32 v9, v14, v15
	s_nop 0
	v_cvt_pk_bf16_f32 v10, v10, v11
	v_cvt_pk_bf16_f32 v11, v16, v17
	global_store_dwordx4 v[76:77], v[8:11], off offset:3328
	s_nop 1
	v_pk_mul_f32 v[8:9], s[10:11], v[2:3]
	v_pk_mul_f32 v[2:3], s[8:9], v[0:1]
	v_cvt_pk_bf16_f32 v0, v4, v5
	v_cvt_pk_bf16_f32 v1, v6, v7
	s_nop 0
	v_cvt_pk_bf16_f32 v2, v2, v3
	v_cvt_pk_bf16_f32 v3, v8, v9
	global_store_dwordx4 v[60:61], v[0:3], off offset:3328
	s_cbranch_vccz .LBB0_636
	s_waitcnt vmcnt(0)
	s_cmpk_gt_u32 s1, 0xff
	s_cbranch_scc1 .LBB0_626
	s_barrier
	s_branch .LBB0_626

.LBB0_656:
	s_add_u32 s20, s18, 0xfff80080
	s_addc_u32 s21, s19, -1
	s_add_i32 s34, 0, 0x10000
	v_add_u32_e32 v152, s34, v174
	ds_read_b128 v[140:143], v152
	ds_read_b128 v[144:147], v152 offset:1024
	ds_read_b128 v[148:151], v152 offset:2048
	ds_read_b128 v[152:155], v152 offset:3072
	s_cmp_eq_u32 s54, 28
	s_cselect_b32 s25, s9, s21
	s_cselect_b32 s24, s15, s20
	s_cselect_b32 s21, s5, s53
	s_cselect_b32 s20, s17, s44
	v_lshl_add_u64 v[180:181], s[18:19], 0, v[136:137]
	s_add_i32 m0, s30, 0xc000
	ds_read_b128 v[156:159], v189
	ds_read_b128 v[160:163], v189 offset:1024
	ds_read_b128 v[164:167], v189 offset:2048
	ds_read_b128 v[168:171], v189 offset:3072
	ds_read_b128 v[190:193], v189 offset:4096
	ds_read_b128 v[194:197], v189 offset:5120
	ds_read_b128 v[198:201], v189 offset:6144
	ds_read_b128 v[208:211], v189 offset:7168
	global_load_lds_dwordx4 v[180:181], off
	v_lshl_add_u64 v[180:181], s[18:19], 0, v[138:139]
	s_add_i32 m0, s30, 0xe000
	s_nop 0
	global_load_lds_dwordx4 v[180:181], off
	s_waitcnt lgkmcnt(8)
	s_barrier
	s_waitcnt lgkmcnt(0)
	s_waitcnt lgkmcnt(0)
	v_mfma_f32_16x16x32_bf16 v[124:127], v[140:143], v[156:159], v[124:127]
	v_mfma_f32_16x16x32_bf16 v[120:123], v[148:151], v[156:159], v[120:123]
	v_mfma_f32_16x16x32_bf16 v[108:111], v[140:143], v[164:167], v[108:111]
	v_mfma_f32_16x16x32_bf16 v[104:107], v[148:151], v[164:167], v[104:107]
	v_mfma_f32_16x16x32_bf16 v[92:95], v[140:143], v[190:193], v[92:95]
	v_mfma_f32_16x16x32_bf16 v[88:91], v[148:151], v[190:193], v[88:91]
	v_mfma_f32_16x16x32_bf16 v[76:79], v[140:143], v[198:201], v[76:79]
	v_mfma_f32_16x16x32_bf16 v[72:75], v[148:151], v[198:201], v[72:75]
	v_mfma_f32_16x16x32_bf16 v[124:127], v[144:147], v[160:163], v[124:127]
	v_mfma_f32_16x16x32_bf16 v[120:123], v[152:155], v[160:163], v[120:123]
	v_mfma_f32_16x16x32_bf16 v[108:111], v[144:147], v[168:171], v[108:111]
	v_mfma_f32_16x16x32_bf16 v[104:107], v[152:155], v[168:171], v[104:107]
	v_mfma_f32_16x16x32_bf16 v[92:95], v[144:147], v[194:197], v[92:95]
	v_mfma_f32_16x16x32_bf16 v[88:91], v[152:155], v[194:197], v[88:91]
	v_mfma_f32_16x16x32_bf16 v[76:79], v[144:147], v[208:211], v[76:79]
	v_mfma_f32_16x16x32_bf16 v[72:75], v[152:155], v[208:211], v[72:75]
	s_barrier
	s_add_i32 s35, 0, 0x14000
	s_add_i32 s34, s34, s28
	v_add_u32_e32 v176, s35, v174
	v_lshl_add_u64 v[180:181], s[20:21], 0, v[130:131]
	s_mov_b32 m0, s34
	ds_read_b128 v[212:215], v176
	ds_read_b128 v[216:219], v176 offset:1024
	ds_read_b128 v[220:223], v176 offset:2048
	ds_read_b128 v[224:227], v176 offset:3072
	global_load_lds_dwordx4 v[180:181], off
	v_lshl_add_u64 v[228:229], s[20:21], 0, v[134:135]
	s_add_i32 m0, s34, 0x2000
	s_nop 0
	global_load_lds_dwordx4 v[228:229], off
	s_barrier
	s_waitcnt lgkmcnt(0)
	s_waitcnt lgkmcnt(0)
	v_mfma_f32_16x16x32_bf16 v[116:119], v[212:215], v[156:159], v[116:119]
	v_mfma_f32_16x16x32_bf16 v[112:115], v[220:223], v[156:159], v[112:115]
	v_mfma_f32_16x16x32_bf16 v[100:103], v[212:215], v[164:167], v[100:103]
	v_mfma_f32_16x16x32_bf16 v[96:99], v[220:223], v[164:167], v[96:99]
	v_mfma_f32_16x16x32_bf16 v[84:87], v[212:215], v[190:193], v[84:87]
	v_mfma_f32_16x16x32_bf16 v[80:83], v[220:223], v[190:193], v[80:83]
	v_mfma_f32_16x16x32_bf16 v[68:71], v[212:215], v[198:201], v[68:71]
	v_mfma_f32_16x16x32_bf16 v[64:67], v[220:223], v[198:201], v[64:67]
	v_mfma_f32_16x16x32_bf16 v[116:119], v[216:219], v[160:163], v[116:119]
	v_mfma_f32_16x16x32_bf16 v[112:115], v[224:227], v[160:163], v[112:115]
	v_mfma_f32_16x16x32_bf16 v[100:103], v[216:219], v[168:171], v[100:103]
	v_mfma_f32_16x16x32_bf16 v[96:99], v[224:227], v[168:171], v[96:99]
	v_mfma_f32_16x16x32_bf16 v[84:87], v[216:219], v[194:197], v[84:87]
	v_mfma_f32_16x16x32_bf16 v[80:83], v[224:227], v[194:197], v[80:83]
	v_mfma_f32_16x16x32_bf16 v[68:71], v[216:219], v[208:211], v[68:71]
	v_mfma_f32_16x16x32_bf16 v[64:67], v[224:227], v[208:211], v[64:67]
	s_mov_b32 m0, s30
	v_lshl_add_u64 v[230:231], s[24:25], 0, v[128:129]
	s_barrier
	ds_read_b128 v[156:159], v189 offset:16384
	ds_read_b128 v[160:163], v189 offset:17408
	ds_read_b128 v[164:167], v189 offset:18432
	ds_read_b128 v[168:171], v189 offset:19456
	ds_read_b128 v[190:193], v189 offset:20480
	ds_read_b128 v[194:197], v189 offset:21504
	ds_read_b128 v[198:201], v189 offset:22528
	ds_read_b128 v[208:211], v189 offset:23552
	global_load_lds_dwordx4 v[230:231], off
	v_lshl_add_u64 v[232:233], s[24:25], 0, v[132:133]
	s_mov_b32 m0, s31
	s_nop 0
	global_load_lds_dwordx4 v[232:233], off
	s_barrier
	s_waitcnt lgkmcnt(0)
	s_waitcnt lgkmcnt(0)
	v_mfma_f32_16x16x32_bf16 v[60:63], v[140:143], v[156:159], v[60:63]
	v_mfma_f32_16x16x32_bf16 v[56:59], v[148:151], v[156:159], v[56:59]
	v_mfma_f32_16x16x32_bf16 v[44:47], v[140:143], v[164:167], v[44:47]
	v_mfma_f32_16x16x32_bf16 v[40:43], v[148:151], v[164:167], v[40:43]
	v_mfma_f32_16x16x32_bf16 v[28:31], v[140:143], v[190:193], v[28:31]
	v_mfma_f32_16x16x32_bf16 v[24:27], v[148:151], v[190:193], v[24:27]
	v_mfma_f32_16x16x32_bf16 v[12:15], v[140:143], v[198:201], v[12:15]
	v_mfma_f32_16x16x32_bf16 v[8:11], v[148:151], v[198:201], v[8:11]
	v_mfma_f32_16x16x32_bf16 v[60:63], v[144:147], v[160:163], v[60:63]
	v_mfma_f32_16x16x32_bf16 v[56:59], v[152:155], v[160:163], v[56:59]
	v_mfma_f32_16x16x32_bf16 v[44:47], v[144:147], v[168:171], v[44:47]
	v_mfma_f32_16x16x32_bf16 v[40:43], v[152:155], v[168:171], v[40:43]
	v_mfma_f32_16x16x32_bf16 v[28:31], v[144:147], v[194:197], v[28:31]
	v_mfma_f32_16x16x32_bf16 v[24:27], v[152:155], v[194:197], v[24:27]
	v_mfma_f32_16x16x32_bf16 v[12:15], v[144:147], v[208:211], v[12:15]
	v_mfma_f32_16x16x32_bf16 v[8:11], v[152:155], v[208:211], v[8:11]
	s_barrier
	s_add_u32 s56, s20, 0x80000
	s_addc_u32 s57, s21, 0
	s_add_i32 s34, s35, s28
	v_lshl_add_u64 v[140:141], s[56:57], 0, v[130:131]
	s_mov_b32 m0, s34
	s_nop 0
	global_load_lds_dwordx4 v[140:141], off
	v_lshl_add_u64 v[140:141], s[56:57], 0, v[134:135]
	s_add_i32 m0, s34, 0x2000
	s_nop 0
	global_load_lds_dwordx4 v[140:141], off
	s_waitcnt vmcnt(6)
	s_barrier
	v_mfma_f32_16x16x32_bf16 v[52:55], v[212:215], v[156:159], v[52:55]
	v_mfma_f32_16x16x32_bf16 v[48:51], v[220:223], v[156:159], v[48:51]
	v_mfma_f32_16x16x32_bf16 v[36:39], v[212:215], v[164:167], v[36:39]
	v_mfma_f32_16x16x32_bf16 v[32:35], v[220:223], v[164:167], v[32:35]
	v_mfma_f32_16x16x32_bf16 v[20:23], v[212:215], v[190:193], v[20:23]
	v_mfma_f32_16x16x32_bf16 v[16:19], v[220:223], v[190:193], v[16:19]
	v_mfma_f32_16x16x32_bf16 v[4:7], v[212:215], v[198:201], v[4:7]
	v_mfma_f32_16x16x32_bf16 v[0:3], v[220:223], v[198:201], v[0:3]
	v_mfma_f32_16x16x32_bf16 v[52:55], v[216:219], v[160:163], v[52:55]
	v_mfma_f32_16x16x32_bf16 v[48:51], v[224:227], v[160:163], v[48:51]
	v_mfma_f32_16x16x32_bf16 v[36:39], v[216:219], v[168:171], v[36:39]
	v_mfma_f32_16x16x32_bf16 v[32:35], v[224:227], v[168:171], v[32:35]
	v_mfma_f32_16x16x32_bf16 v[20:23], v[216:219], v[194:197], v[20:23]
	v_mfma_f32_16x16x32_bf16 v[16:19], v[224:227], v[194:197], v[16:19]
	v_mfma_f32_16x16x32_bf16 v[4:7], v[216:219], v[208:211], v[4:7]
	v_mfma_f32_16x16x32_bf16 v[0:3], v[224:227], v[208:211], v[0:3]
	s_add_i32 s34, 0, 0x18000
	v_add_u32_e32 v152, s34, v174
	s_barrier
	ds_read_b128 v[140:143], v152
	ds_read_b128 v[144:147], v152 offset:1024
	ds_read_b128 v[148:151], v152 offset:2048
	ds_read_b128 v[152:155], v152 offset:3072
	s_add_u32 s24, s24, 0x80000
	s_addc_u32 s25, s25, 0
	s_mov_b32 m0, s33
	v_lshl_add_u64 v[212:213], s[24:25], 0, v[128:129]
	ds_read_b128 v[156:159], v189 offset:32768
	ds_read_b128 v[160:163], v189 offset:33792
	ds_read_b128 v[164:167], v189 offset:34816
	ds_read_b128 v[168:171], v189 offset:35840
	ds_read_b128 v[190:193], v189 offset:36864
	ds_read_b128 v[194:197], v189 offset:37888
	ds_read_b128 v[198:201], v189 offset:38912
	ds_read_b128 v[208:211], v189 offset:39936
	global_load_lds_dwordx4 v[212:213], off
	v_lshl_add_u64 v[212:213], s[24:25], 0, v[132:133]
	s_mov_b32 m0, s37
	s_nop 0
	global_load_lds_dwordx4 v[212:213], off
	s_waitcnt lgkmcnt(8)
	s_barrier
	s_waitcnt lgkmcnt(0)
	s_waitcnt lgkmcnt(0)
	v_mfma_f32_16x16x32_bf16 v[124:127], v[140:143], v[156:159], v[124:127]
	v_mfma_f32_16x16x32_bf16 v[120:123], v[148:151], v[156:159], v[120:123]
	v_mfma_f32_16x16x32_bf16 v[108:111], v[140:143], v[164:167], v[108:111]
	v_mfma_f32_16x16x32_bf16 v[104:107], v[148:151], v[164:167], v[104:107]
	v_mfma_f32_16x16x32_bf16 v[92:95], v[140:143], v[190:193], v[92:95]
	v_mfma_f32_16x16x32_bf16 v[88:91], v[148:151], v[190:193], v[88:91]
	v_mfma_f32_16x16x32_bf16 v[76:79], v[140:143], v[198:201], v[76:79]
	v_mfma_f32_16x16x32_bf16 v[72:75], v[148:151], v[198:201], v[72:75]
	v_mfma_f32_16x16x32_bf16 v[124:127], v[144:147], v[160:163], v[124:127]
	v_mfma_f32_16x16x32_bf16 v[120:123], v[152:155], v[160:163], v[120:123]
	v_mfma_f32_16x16x32_bf16 v[108:111], v[144:147], v[168:171], v[108:111]
	v_mfma_f32_16x16x32_bf16 v[104:107], v[152:155], v[168:171], v[104:107]
	v_mfma_f32_16x16x32_bf16 v[92:95], v[144:147], v[194:197], v[92:95]
	v_mfma_f32_16x16x32_bf16 v[88:91], v[152:155], v[194:197], v[88:91]
	v_mfma_f32_16x16x32_bf16 v[76:79], v[144:147], v[208:211], v[76:79]
	v_mfma_f32_16x16x32_bf16 v[72:75], v[152:155], v[208:211], v[72:75]
	s_barrier
	s_add_i32 s24, 0, 0x1c000
	s_add_i32 s25, s34, s28
	v_add_u32_e32 v176, s24, v174
	v_lshl_add_u64 v[180:181], v[180:181], 0, s[40:41]
	s_mov_b32 m0, s25
	ds_read_b128 v[212:215], v176
	ds_read_b128 v[216:219], v176 offset:1024
	ds_read_b128 v[220:223], v176 offset:2048
	ds_read_b128 v[224:227], v176 offset:3072
	global_load_lds_dwordx4 v[180:181], off
	v_lshl_add_u64 v[180:181], v[228:229], 0, s[40:41]
	s_add_i32 m0, s25, 0x2000
	s_nop 0
	global_load_lds_dwordx4 v[180:181], off
	s_barrier
	s_waitcnt lgkmcnt(0)
	s_waitcnt lgkmcnt(0)
	v_mfma_f32_16x16x32_bf16 v[116:119], v[212:215], v[156:159], v[116:119]
	v_mfma_f32_16x16x32_bf16 v[112:115], v[220:223], v[156:159], v[112:115]
	v_mfma_f32_16x16x32_bf16 v[100:103], v[212:215], v[164:167], v[100:103]
	v_mfma_f32_16x16x32_bf16 v[96:99], v[220:223], v[164:167], v[96:99]
	v_mfma_f32_16x16x32_bf16 v[84:87], v[212:215], v[190:193], v[84:87]
	v_mfma_f32_16x16x32_bf16 v[80:83], v[220:223], v[190:193], v[80:83]
	v_mfma_f32_16x16x32_bf16 v[68:71], v[212:215], v[198:201], v[68:71]
	v_mfma_f32_16x16x32_bf16 v[64:67], v[220:223], v[198:201], v[64:67]
	v_mfma_f32_16x16x32_bf16 v[116:119], v[216:219], v[160:163], v[116:119]
	v_mfma_f32_16x16x32_bf16 v[112:115], v[224:227], v[160:163], v[112:115]
	v_mfma_f32_16x16x32_bf16 v[100:103], v[216:219], v[168:171], v[100:103]
	v_mfma_f32_16x16x32_bf16 v[96:99], v[224:227], v[168:171], v[96:99]
	v_mfma_f32_16x16x32_bf16 v[84:87], v[216:219], v[194:197], v[84:87]
	v_mfma_f32_16x16x32_bf16 v[80:83], v[224:227], v[194:197], v[80:83]
	v_mfma_f32_16x16x32_bf16 v[68:71], v[216:219], v[208:211], v[68:71]
	v_mfma_f32_16x16x32_bf16 v[64:67], v[224:227], v[208:211], v[64:67]
	s_mov_b32 m0, s47
	v_lshl_add_u64 v[180:181], v[230:231], 0, s[40:41]
	s_barrier
	ds_read_b128 v[156:159], v189 offset:49152
	ds_read_b128 v[160:163], v189 offset:50176
	ds_read_b128 v[164:167], v189 offset:51200
	ds_read_b128 v[168:171], v189 offset:52224
	ds_read_b128 v[190:193], v189 offset:53248
	ds_read_b128 v[194:197], v189 offset:54272
	ds_read_b128 v[198:201], v189 offset:55296
	ds_read_b128 v[208:211], v189 offset:56320
	global_load_lds_dwordx4 v[180:181], off
	v_lshl_add_u64 v[180:181], v[232:233], 0, s[40:41]
	s_mov_b32 m0, s48
	s_nop 0
	global_load_lds_dwordx4 v[180:181], off
	s_barrier
	s_waitcnt lgkmcnt(0)
	s_waitcnt lgkmcnt(0)
	v_mfma_f32_16x16x32_bf16 v[60:63], v[140:143], v[156:159], v[60:63]
	v_mfma_f32_16x16x32_bf16 v[56:59], v[148:151], v[156:159], v[56:59]
	v_mfma_f32_16x16x32_bf16 v[44:47], v[140:143], v[164:167], v[44:47]
	v_mfma_f32_16x16x32_bf16 v[40:43], v[148:151], v[164:167], v[40:43]
	v_mfma_f32_16x16x32_bf16 v[28:31], v[140:143], v[190:193], v[28:31]
	v_mfma_f32_16x16x32_bf16 v[24:27], v[148:151], v[190:193], v[24:27]
	v_mfma_f32_16x16x32_bf16 v[12:15], v[140:143], v[198:201], v[12:15]
	v_mfma_f32_16x16x32_bf16 v[8:11], v[148:151], v[198:201], v[8:11]
	v_mfma_f32_16x16x32_bf16 v[60:63], v[144:147], v[160:163], v[60:63]
	v_mfma_f32_16x16x32_bf16 v[56:59], v[152:155], v[160:163], v[56:59]
	v_mfma_f32_16x16x32_bf16 v[44:47], v[144:147], v[168:171], v[44:47]
	v_mfma_f32_16x16x32_bf16 v[40:43], v[152:155], v[168:171], v[40:43]
	v_mfma_f32_16x16x32_bf16 v[28:31], v[144:147], v[194:197], v[28:31]
	v_mfma_f32_16x16x32_bf16 v[24:27], v[152:155], v[194:197], v[24:27]
	v_mfma_f32_16x16x32_bf16 v[12:15], v[144:147], v[208:211], v[12:15]
	v_mfma_f32_16x16x32_bf16 v[8:11], v[152:155], v[208:211], v[8:11]
	s_barrier
	s_add_u32 s20, s20, 0x80080
	s_addc_u32 s21, s21, 0
	s_add_i32 s24, s24, s28
	v_lshl_add_u64 v[140:141], s[20:21], 0, v[130:131]
	s_mov_b32 m0, s24
	s_nop 0
	global_load_lds_dwordx4 v[140:141], off
	v_lshl_add_u64 v[140:141], s[20:21], 0, v[134:135]
	s_add_i32 m0, s24, 0x2000
	s_nop 0
	global_load_lds_dwordx4 v[140:141], off
	s_waitcnt vmcnt(6)
	s_barrier
	v_mfma_f32_16x16x32_bf16 v[52:55], v[212:215], v[156:159], v[52:55]
	v_mfma_f32_16x16x32_bf16 v[48:51], v[220:223], v[156:159], v[48:51]
	v_mfma_f32_16x16x32_bf16 v[36:39], v[212:215], v[164:167], v[36:39]
	v_mfma_f32_16x16x32_bf16 v[32:35], v[220:223], v[164:167], v[32:35]
	v_mfma_f32_16x16x32_bf16 v[20:23], v[212:215], v[190:193], v[20:23]
	v_mfma_f32_16x16x32_bf16 v[16:19], v[220:223], v[190:193], v[16:19]
	v_mfma_f32_16x16x32_bf16 v[4:7], v[212:215], v[198:201], v[4:7]
	v_mfma_f32_16x16x32_bf16 v[0:3], v[220:223], v[198:201], v[0:3]
	v_mfma_f32_16x16x32_bf16 v[52:55], v[216:219], v[160:163], v[52:55]
	v_mfma_f32_16x16x32_bf16 v[48:51], v[224:227], v[160:163], v[48:51]
	v_mfma_f32_16x16x32_bf16 v[36:39], v[216:219], v[168:171], v[36:39]
	v_mfma_f32_16x16x32_bf16 v[32:35], v[224:227], v[168:171], v[32:35]
	v_mfma_f32_16x16x32_bf16 v[20:23], v[216:219], v[194:197], v[20:23]
	v_mfma_f32_16x16x32_bf16 v[16:19], v[224:227], v[194:197], v[16:19]
	v_mfma_f32_16x16x32_bf16 v[4:7], v[216:219], v[208:211], v[4:7]
	v_mfma_f32_16x16x32_bf16 v[0:3], v[224:227], v[208:211], v[0:3]
	s_add_i32 s54, s54, 2
	s_add_u32 s44, s44, 0x100
	s_addc_u32 s53, s53, 0
	s_add_u32 s18, s18, 0x100
	s_addc_u32 s19, s19, 0
	s_cmp_gt_u32 s54, 29
	s_barrier
	s_cbranch_scc0 .LBB0_656
	s_lshl_b32 s5, s16, 8
	s_cmp_lt_i32 s14, 18
	v_readlane_b32 s20, v255, 32
	s_cselect_b64 s[18:19], -1, 0
	v_readlane_b32 s21, v255, 33
	s_or_b64 s[20:21], s[20:21], s[18:19]
	s_mov_b64 s[18:19], -1
	s_and_b64 vcc, exec, s[20:21]
	v_mov_b32_e32 v198, 0xbf1f24be
	s_cbranch_vccnz .LBB0_664
	s_sub_i32 s9, s14, 18
	s_cmp_gt_i32 s16, 31
	s_cbranch_scc0 .LBB0_660
	s_sub_i32 s15, s16, 32
	s_lshr_b32 s15, s15, 1
	s_and_b32 s15, s15, 0x1fffffc
	s_add_i32 s15, s15, s9
	s_lshl_b32 s44, s15, 7
	s_lshl_b64 s[18:19], s[44:45], 13
	s_add_u32 s24, s38, s18
	s_addc_u32 s25, s39, s19
	s_and_b32 s15, s5, 0x700
	s_add_i32 s15, s15, s46
	s_mov_b64 s[18:19], 0
